# EpiResid epilogues: bf16 row-piece stores paired into 16-byte stores via permlane16 swaps (28 of 32 groups), wait counts recomputed
# speedup vs baseline: 1.0040x; 1.0040x over previous
; #define PG8_GAS __attribute__((address_space(1)))
; __device__ __forceinline__ unsigned pk2_(float lo, float hi) { f32x2c_t v = {lo, hi}; bf16x2c_t b = __builtin_convertvector(v, bf16x2c_t); return __builtin_bit_cast(unsigned, b); }
;     __device__ __forceinline__ void operator()(const f32x4 (&acc)[2][2][4][2], const Unit& u, int wr, int wc, int fr, int fq) const {
;         typedef unsigned u32x2v __attribute__((ext_vector_type(2)));
;         const int row0 = u.pm * BM + wr * 64 + fr, col0 = u.pn * BM + wc * 32 + 4 * fq;
;         u32x2v bsv[2][4][2][2];
; #pragma unroll
;         for (int ai = 0; ai < 2; ++ai)
; #pragma unroll
;             for (int m = 0; m < 4; ++m) { const size_t off = (size_t)(row0 + ai * HALF + m * 16) * 1024 + col0;
; #pragma unroll
;                 for (int bj = 0; bj < 2; ++bj)
; #pragma unroll
;                     for (int n = 0; n < 2; ++n) bsv[ai][m][bj][n] = *(const PG8_GAS u32x2v*)(hbase + off + bj * HALF + n * 16); }
; #pragma unroll
;         for (int ai = 0; ai < 2; ++ai)
; #pragma unroll
;             for (int m = 0; m < 4; ++m) {
;                 const int r = row0 + ai * HALF + m * 16; const size_t off = (size_t)r * 1024 + col0; float ss = 0.f;
; #pragma unroll
;                 for (int bj = 0; bj < 2; ++bj)
; #pragma unroll
;                     for (int n = 0; n < 2; ++n) {
;                         const u32x2v w0 = bsv[ai][m][bj][n]; f32x4 bs;
;                         bs[0] = __builtin_bit_cast(float, w0.x << 16); bs[1] = __builtin_bit_cast(float, w0.x & 0xffff0000u); bs[2] = __builtin_bit_cast(float, w0.y << 16); bs[3] = __builtin_bit_cast(float, w0.y & 0xffff0000u);
;                         const f32x4 v = bs + acc[ai][bj][m][n] * alpha;
;                         { u32x2v w; w.x = pk2_(v[0], v[1]); w.y = pk2_(v[2], v[3]); *(PG8_GAS u32x2v*)(hb + off + bj * HALF + n * 16) = w; }
;                         ss += (v[0] * v[0] + v[1] * v[1]) + (v[2] * v[2] + v[3] * v[3]);
;                     }
;                 ss += __shfl_xor(ss, 16); ss += __shfl_xor(ss, 32);
;                 if (fq == 0) ((PG8_GAS float*)parts)[(size_t)r * 16 + u.pn * 4 + wc] = ss;
;             }
;     }
.LBB0_771:
	s_lshl_b32 s34, s58, 8
	v_mov_b32_e32 v136, v252
	s_add_i32 s34, s34, s49
	v_and_b32_e32 v233, 64, v231
	v_and_or_b32 v220, v136, 15, s34
	s_lshl_b32 s34, s12, 8
	v_bfe_u32 v224, v136, 4, 2
	s_or_b32 s34, s34, s50
	v_lshl_or_b32 v138, v224, 2, s34
	v_ashrrev_i32_e32 v139, 31, v138
	v_lshlrev_b64 v[234:235], 1, v[138:139]
	v_ashrrev_i32_e32 v221, 31, v220
	v_lshl_add_u64 v[140:141], s[14:15], 0, v[234:235]
	v_lshlrev_b64 v[236:237], 11, v[220:221]
	v_lshl_add_u64 v[136:137], v[140:141], 0, v[236:237]
	global_load_dwordx2 v[238:239], v[136:137], off
	global_load_dwordx2 v[240:241], v[136:137], off offset:32
	global_load_dwordx2 v[242:243], v[136:137], off offset:256
	global_load_dwordx2 v[244:245], v[136:137], off offset:288
	v_or_b32_e32 v208, 16, v220
	v_ashrrev_i32_e32 v209, 31, v208
	v_or_b32_e32 v196, 32, v220
	v_lshlrev_b64 v[218:219], 11, v[208:209]
	v_ashrrev_i32_e32 v197, 31, v196
	v_or_b32_e32 v184, 48, v220
	v_lshl_add_u64 v[136:137], v[140:141], 0, v[218:219]
	v_lshlrev_b64 v[206:207], 11, v[196:197]
	v_ashrrev_i32_e32 v185, 31, v184
	v_add_u32_e32 v172, 0x80, v220
	global_load_dwordx2 v[222:223], v[136:137], off
	global_load_dwordx2 v[216:217], v[136:137], off offset:32
	global_load_dwordx2 v[214:215], v[136:137], off offset:256
	global_load_dwordx2 v[212:213], v[136:137], off offset:288
	v_lshl_add_u64 v[136:137], v[140:141], 0, v[206:207]
	v_lshlrev_b64 v[194:195], 11, v[184:185]
	v_ashrrev_i32_e32 v173, 31, v172
	v_add_u32_e32 v160, 0x90, v220
	global_load_dwordx2 v[210:211], v[136:137], off
	global_load_dwordx2 v[204:205], v[136:137], off offset:32
	global_load_dwordx2 v[202:203], v[136:137], off offset:256
	global_load_dwordx2 v[200:201], v[136:137], off offset:288
	v_lshl_add_u64 v[136:137], v[140:141], 0, v[194:195]
	v_lshlrev_b64 v[182:183], 11, v[172:173]
	v_ashrrev_i32_e32 v161, 31, v160
	v_add_u32_e32 v148, 0xa0, v220
	global_load_dwordx2 v[198:199], v[136:137], off
	global_load_dwordx2 v[192:193], v[136:137], off offset:32
	global_load_dwordx2 v[190:191], v[136:137], off offset:256
	global_load_dwordx2 v[188:189], v[136:137], off offset:288
	v_lshl_add_u64 v[136:137], v[140:141], 0, v[182:183]
	v_lshlrev_b64 v[170:171], 11, v[160:161]
	v_ashrrev_i32_e32 v149, 31, v148
	global_load_dwordx2 v[186:187], v[136:137], off
	global_load_dwordx2 v[180:181], v[136:137], off offset:32
	global_load_dwordx2 v[178:179], v[136:137], off offset:256
	global_load_dwordx2 v[176:177], v[136:137], off offset:288
	v_lshl_add_u64 v[136:137], v[140:141], 0, v[170:171]
	v_lshlrev_b64 v[158:159], 11, v[148:149]
	global_load_dwordx2 v[174:175], v[136:137], off
	global_load_dwordx2 v[168:169], v[136:137], off offset:32
	global_load_dwordx2 v[166:167], v[136:137], off offset:256
	global_load_dwordx2 v[164:165], v[136:137], off offset:288
	v_lshl_add_u64 v[136:137], v[140:141], 0, v[158:159]
	global_load_dwordx2 v[162:163], v[136:137], off
	global_load_dwordx2 v[156:157], v[136:137], off offset:32
	global_load_dwordx2 v[154:155], v[136:137], off offset:256
	global_load_dwordx2 v[152:153], v[136:137], off offset:288
	v_add_u32_e32 v136, 0xb0, v220
	v_ashrrev_i32_e32 v137, 31, v136
	v_lshlrev_b64 v[146:147], 11, v[136:137]
	v_lshl_add_u64 v[140:141], v[140:141], 0, v[146:147]
	global_load_dwordx2 v[150:151], v[140:141], off
	global_load_dwordx2 v[144:145], v[140:141], off offset:32
	global_load_dwordx2 v[142:143], v[140:141], off offset:256
	s_nop 0
	global_load_dwordx2 v[140:141], v[140:141], off offset:288
	v_bfe_u32 v250, v252, 4, 1
	v_mul_u32_u24_e32 v250, 24, v250
	v_mov_b32_e32 v251, 0
	v_xor_b32_e32 v232, 16, v231
	v_add_u32_e32 v233, 64, v233
	v_xor_b32_e32 v246, 32, v231
	v_cmp_lt_i32_e32 vcc, v232, v233
	v_lshl_add_u64 v[236:237], s[16:17], 0, v[236:237]
	s_lshl_b32 s34, s12, 2
	v_cndmask_b32_e32 v232, v231, v232, vcc
	v_cmp_lt_i32_e32 vcc, v246, v233
	v_lshlrev_b32_e32 v233, 2, v232
	v_lshl_add_u64 v[234:235], v[236:237], 0, v[234:235]
	v_cndmask_b32_e32 v246, v231, v246, vcc
	v_lshlrev_b32_e32 v232, 2, v246
	v_cmp_eq_u32_e32 vcc, 0, v224
	s_ashr_i32 s35, s34, 31
	s_waitcnt vmcnt(28)
	v_lshlrev_b32_e32 v246, 16, v238
	v_and_b32_e32 v247, 0xffff0000, v238
	v_lshlrev_b32_e32 v238, 16, v239
	v_and_b32_e32 v239, 0xffff0000, v239
	v_pk_fma_f32 v[124:125], v[124:125], 0.5, v[246:247] op_sel_hi:[1,0,1]
	v_pk_fma_f32 v[126:127], v[126:127], 0.5, v[238:239] op_sel_hi:[1,0,1]
	v_cvt_pk_bf16_f32 v238, v124, v125
	v_mul_f32_e32 v125, v125, v125
	v_fmac_f32_e32 v125, v124, v124
	v_mul_f32_e32 v124, v127, v127
	v_fmac_f32_e32 v124, v126, v126
	v_add_f32_e32 v224, v125, v124
	v_lshlrev_b32_e32 v124, 16, v240
	v_and_b32_e32 v125, 0xffff0000, v240
	v_cvt_pk_bf16_f32 v239, v126, v127
	v_lshlrev_b32_e32 v126, 16, v241
	v_and_b32_e32 v127, 0xffff0000, v241
	v_pk_fma_f32 v[120:121], v[120:121], 0.5, v[124:125] op_sel_hi:[1,0,1]
	v_pk_fma_f32 v[122:123], v[122:123], 0.5, v[126:127] op_sel_hi:[1,0,1]
	v_cvt_pk_bf16_f32 v124, v120, v121
	v_mul_f32_e32 v121, v121, v121
	v_fmac_f32_e32 v121, v120, v120
	v_mul_f32_e32 v120, v123, v123
	v_fmac_f32_e32 v120, v122, v122
	v_add_f32_e32 v120, v121, v120
	v_add_f32_e32 v125, v224, v120
	v_lshlrev_b32_e32 v120, 16, v242
	v_and_b32_e32 v121, 0xffff0000, v242
	v_lshlrev_b32_e32 v126, 16, v243
	v_and_b32_e32 v127, 0xffff0000, v243
	v_pk_fma_f32 v[118:119], v[118:119], 0.5, v[126:127] op_sel_hi:[1,0,1]
	v_pk_fma_f32 v[116:117], v[116:117], 0.5, v[120:121] op_sel_hi:[1,0,1]
	v_mul_f32_e32 v121, v119, v119
	v_mul_f32_e32 v120, v117, v117
	v_fmac_f32_e32 v120, v116, v116
	v_fmac_f32_e32 v121, v118, v118
	v_add_f32_e32 v120, v120, v121
	v_add_f32_e32 v125, v125, v120
	v_lshlrev_b32_e32 v120, 16, v244
	v_and_b32_e32 v121, 0xffff0000, v244
	v_lshlrev_b32_e32 v126, 16, v245
	v_and_b32_e32 v127, 0xffff0000, v245
	v_pk_fma_f32 v[114:115], v[114:115], 0.5, v[126:127] op_sel_hi:[1,0,1]
	v_pk_fma_f32 v[120:121], v[112:113], 0.5, v[120:121] op_sel_hi:[1,0,1]
	v_mul_f32_e32 v113, v115, v115
	v_mul_f32_e32 v112, v121, v121
	v_fmac_f32_e32 v112, v120, v120
	v_fmac_f32_e32 v113, v114, v114
	v_add_f32_e32 v112, v112, v113
	v_add_f32_e32 v112, v125, v112
	v_mov_b32_e32 v113, v112
	s_nop 1
	v_permlane16_swap_b32_e32 v112, v113
	v_cvt_pk_bf16_f32 v116, v116, v117
	v_cvt_pk_bf16_f32 v117, v118, v119
	v_cvt_pk_bf16_f32 v125, v122, v123
	global_store_dwordx2 v[234:235], v[116:117], off offset:256
	s_waitcnt lgkmcnt(0)
	v_add_f32_e32 v112, v112, v113
	v_mov_b32_e32 v113, v112
	s_nop 1
	v_permlane32_swap_b32_e32 v112, v113
	v_cvt_pk_bf16_f32 v116, v120, v121
	v_cvt_pk_bf16_f32 v117, v114, v115
	global_store_dwordx2 v[234:235], v[238:239], off
	global_store_dwordx2 v[234:235], v[124:125], off offset:32
	global_store_dwordx2 v[234:235], v[116:117], off offset:288
	s_and_saveexec_b64 s[36:37], vcc
	s_cbranch_execz .LBB0_773
; #define PG8_GAS __attribute__((address_space(1)))
; __device__ __forceinline__ unsigned pk2_(float lo, float hi) { f32x2c_t v = {lo, hi}; bf16x2c_t b = __builtin_convertvector(v, bf16x2c_t); return __builtin_bit_cast(unsigned, b); }
;     __device__ __forceinline__ void operator()(const f32x4 (&acc)[2][2][4][2], const Unit& u, int wr, int wc, int fr, int fq) const {
;     ...
;         for (int ai = 0; ai < 2; ++ai)
; #pragma unroll
;             for (int m = 0; m < 4; ++m) {
;                 const int r = row0 + ai * HALF + m * 16; const size_t off = (size_t)r * 1024 + col0; float ss = 0.f;
; #pragma unroll
;                 for (int bj = 0; bj < 2; ++bj)
; #pragma unroll
;                     for (int n = 0; n < 2; ++n) {
;                         const u32x2v w0 = bsv[ai][m][bj][n]; f32x4 bs;
;                         bs[0] = __builtin_bit_cast(float, w0.x << 16); bs[1] = __builtin_bit_cast(float, w0.x & 0xffff0000u); bs[2] = __builtin_bit_cast(float, w0.y << 16); bs[3] = __builtin_bit_cast(float, w0.y & 0xffff0000u);
;                         const f32x4 v = bs + acc[ai][bj][m][n] * alpha;
;                         { u32x2v w; w.x = pk2_(v[0], v[1]); w.y = pk2_(v[2], v[3]); *(PG8_GAS u32x2v*)(hb + off + bj * HALF + n * 16) = w; }
;                         ss += (v[0] * v[0] + v[1] * v[1]) + (v[2] * v[2] + v[3] * v[3]);
;                     }
;                 ss += __shfl_xor(ss, 16); ss += __shfl_xor(ss, 32);
;                 if (fq == 0) ((PG8_GAS float*)parts)[(size_t)r * 16 + u.pn * 4 + wc] = ss;
;             }
	v_lshlrev_b64 v[114:115], 6, v[220:221]
	v_lshl_add_u64 v[114:115], s[18:19], 0, v[114:115]
	v_lshl_add_u64 v[114:115], s[34:35], 2, v[114:115]
	s_lshl_b32 s12, s48, 2
	v_lshl_add_u64 v[114:115], v[114:115], 0, s[12:13]
	s_waitcnt lgkmcnt(0)
	v_add_f32_e32 v112, v112, v113
	global_store_dword v[114:115], v112, off
.LBB0_773:
	s_or_b64 exec, exec, s[36:37]
	s_waitcnt vmcnt(28)
	v_lshlrev_b32_e32 v112, 16, v222
	s_waitcnt lgkmcnt(0)
	v_and_b32_e32 v113, 0xffff0000, v222
	v_lshlrev_b32_e32 v114, 16, v223
	v_and_b32_e32 v115, 0xffff0000, v223
	v_pk_fma_f32 v[108:109], v[108:109], 0.5, v[112:113] op_sel_hi:[1,0,1]
	v_pk_fma_f32 v[110:111], v[110:111], 0.5, v[114:115] op_sel_hi:[1,0,1]
	v_cvt_pk_bf16_f32 v116, v108, v109
	v_mul_f32_e32 v109, v109, v109
	v_lshl_add_u64 v[114:115], s[16:17], 0, v[218:219]
	v_fmac_f32_e32 v109, v108, v108
	v_mul_f32_e32 v108, v111, v111
	v_cvt_pk_bf16_f32 v117, v110, v111
	v_lshl_add_u64 v[114:115], v[138:139], 1, v[114:115]
	v_fmac_f32_e32 v108, v110, v110
	v_add_f32_e32 v112, v109, v108
	v_lshlrev_b32_e32 v108, 16, v216
	v_and_b32_e32 v109, 0xffff0000, v216
	v_lshlrev_b32_e32 v110, 16, v217
	v_and_b32_e32 v111, 0xffff0000, v217
	v_pk_fma_f32 v[104:105], v[104:105], 0.5, v[108:109] op_sel_hi:[1,0,1]
	v_pk_fma_f32 v[106:107], v[106:107], 0.5, v[110:111] op_sel_hi:[1,0,1]
	v_cvt_pk_bf16_f32 v118, v104, v105
	v_mul_f32_e32 v105, v105, v105
	v_fmac_f32_e32 v105, v104, v104
	v_mul_f32_e32 v104, v107, v107
	v_fmac_f32_e32 v104, v106, v106
	v_add_f32_e32 v104, v105, v104
	v_add_f32_e32 v109, v112, v104
	v_lshlrev_b32_e32 v104, 16, v214
	v_and_b32_e32 v105, 0xffff0000, v214
	v_lshlrev_b32_e32 v110, 16, v215
	v_and_b32_e32 v111, 0xffff0000, v215
	v_pk_fma_f32 v[102:103], v[102:103], 0.5, v[110:111] op_sel_hi:[1,0,1]
	v_pk_fma_f32 v[100:101], v[100:101], 0.5, v[104:105] op_sel_hi:[1,0,1]
	v_mul_f32_e32 v105, v103, v103
	v_mul_f32_e32 v104, v101, v101
	v_fmac_f32_e32 v104, v100, v100
	v_fmac_f32_e32 v105, v102, v102
	v_add_f32_e32 v104, v104, v105
	v_add_f32_e32 v109, v109, v104
	v_lshlrev_b32_e32 v104, 16, v212
	v_and_b32_e32 v105, 0xffff0000, v212
	v_lshlrev_b32_e32 v110, 16, v213
	v_and_b32_e32 v111, 0xffff0000, v213
	v_pk_fma_f32 v[98:99], v[98:99], 0.5, v[110:111] op_sel_hi:[1,0,1]
	v_pk_fma_f32 v[104:105], v[96:97], 0.5, v[104:105] op_sel_hi:[1,0,1]
	v_mul_f32_e32 v97, v99, v99
	v_mul_f32_e32 v96, v105, v105
	v_fmac_f32_e32 v96, v104, v104
	v_fmac_f32_e32 v97, v98, v98
	v_add_f32_e32 v96, v96, v97
	v_add_f32_e32 v96, v109, v96
	v_mov_b32_e32 v97, v96
	s_nop 1
	v_permlane16_swap_b32_e32 v96, v97
	v_cvt_pk_bf16_f32 v110, v100, v101
	v_cvt_pk_bf16_f32 v111, v102, v103
	v_cvt_pk_bf16_f32 v119, v106, v107
	s_waitcnt lgkmcnt(0)
	v_add_f32_e32 v96, v96, v97
	v_mov_b32_e32 v97, v96
	s_nop 1
	v_permlane32_swap_b32_e32 v96, v97
	v_cvt_pk_bf16_f32 v112, v104, v105
	v_cvt_pk_bf16_f32 v113, v98, v99
	v_lshl_add_u64 v[114:115], v[114:115], 0, v[250:251]
	s_nop 1
	v_permlane16_swap_b32_e32 v116, v118
	v_permlane16_swap_b32_e32 v117, v119
	global_store_dwordx4 v[114:115], v[116:119], off
	s_nop 1
	s_nop 1
	v_permlane16_swap_b32_e32 v110, v112
	v_permlane16_swap_b32_e32 v111, v113
	global_store_dwordx4 v[114:115], v[110:113], off offset:256
	s_nop 1
	s_and_saveexec_b64 s[36:37], vcc
	s_cbranch_execz .LBB0_775
	v_lshlrev_b64 v[98:99], 6, v[208:209]
	v_lshl_add_u64 v[98:99], s[18:19], 0, v[98:99]
	v_lshl_add_u64 v[98:99], s[34:35], 2, v[98:99]
	s_lshl_b32 s12, s48, 2
	v_lshl_add_u64 v[98:99], v[98:99], 0, s[12:13]
	s_waitcnt lgkmcnt(0)
	v_add_f32_e32 v96, v96, v97
	global_store_dword v[98:99], v96, off
.LBB0_775:
	s_or_b64 exec, exec, s[36:37]
	s_waitcnt vmcnt(26)
	v_lshlrev_b32_e32 v96, 16, v210
	s_waitcnt lgkmcnt(0)
	v_and_b32_e32 v97, 0xffff0000, v210
	v_lshlrev_b32_e32 v98, 16, v211
	v_and_b32_e32 v99, 0xffff0000, v211
	v_pk_fma_f32 v[92:93], v[92:93], 0.5, v[96:97] op_sel_hi:[1,0,1]
	v_pk_fma_f32 v[94:95], v[94:95], 0.5, v[98:99] op_sel_hi:[1,0,1]
	v_cvt_pk_bf16_f32 v100, v92, v93
	v_mul_f32_e32 v93, v93, v93
	v_lshl_add_u64 v[98:99], s[16:17], 0, v[206:207]
	v_fmac_f32_e32 v93, v92, v92
	v_mul_f32_e32 v92, v95, v95
	v_cvt_pk_bf16_f32 v101, v94, v95
	v_lshl_add_u64 v[98:99], v[138:139], 1, v[98:99]
	v_fmac_f32_e32 v92, v94, v94
	v_add_f32_e32 v96, v93, v92
	v_lshlrev_b32_e32 v92, 16, v204
	v_and_b32_e32 v93, 0xffff0000, v204
	v_lshlrev_b32_e32 v94, 16, v205
	v_and_b32_e32 v95, 0xffff0000, v205
	v_pk_fma_f32 v[88:89], v[88:89], 0.5, v[92:93] op_sel_hi:[1,0,1]
	v_pk_fma_f32 v[90:91], v[90:91], 0.5, v[94:95] op_sel_hi:[1,0,1]
	v_cvt_pk_bf16_f32 v102, v88, v89
	v_mul_f32_e32 v89, v89, v89
	v_fmac_f32_e32 v89, v88, v88
	v_mul_f32_e32 v88, v91, v91
	v_fmac_f32_e32 v88, v90, v90
	v_add_f32_e32 v88, v89, v88
	v_add_f32_e32 v93, v96, v88
	v_lshlrev_b32_e32 v88, 16, v202
	v_and_b32_e32 v89, 0xffff0000, v202
	v_lshlrev_b32_e32 v94, 16, v203
	v_and_b32_e32 v95, 0xffff0000, v203
	v_pk_fma_f32 v[86:87], v[86:87], 0.5, v[94:95] op_sel_hi:[1,0,1]
	v_pk_fma_f32 v[84:85], v[84:85], 0.5, v[88:89] op_sel_hi:[1,0,1]
	v_mul_f32_e32 v89, v87, v87
	v_mul_f32_e32 v88, v85, v85
	v_fmac_f32_e32 v88, v84, v84
	v_fmac_f32_e32 v89, v86, v86
	v_add_f32_e32 v88, v88, v89
	v_add_f32_e32 v93, v93, v88
	v_lshlrev_b32_e32 v88, 16, v200
	v_and_b32_e32 v89, 0xffff0000, v200
	v_lshlrev_b32_e32 v94, 16, v201
	v_and_b32_e32 v95, 0xffff0000, v201
	v_pk_fma_f32 v[82:83], v[82:83], 0.5, v[94:95] op_sel_hi:[1,0,1]
	v_pk_fma_f32 v[88:89], v[80:81], 0.5, v[88:89] op_sel_hi:[1,0,1]
	v_mul_f32_e32 v81, v83, v83
	v_mul_f32_e32 v80, v89, v89
	v_fmac_f32_e32 v80, v88, v88
	v_fmac_f32_e32 v81, v82, v82
	v_add_f32_e32 v80, v80, v81
	v_add_f32_e32 v80, v93, v80
	v_mov_b32_e32 v81, v80
	s_nop 1
	v_permlane16_swap_b32_e32 v80, v81
	v_cvt_pk_bf16_f32 v94, v84, v85
	v_cvt_pk_bf16_f32 v95, v86, v87
	v_cvt_pk_bf16_f32 v103, v90, v91
	s_waitcnt lgkmcnt(0)
	v_add_f32_e32 v80, v80, v81
	v_mov_b32_e32 v81, v80
	s_nop 1
	v_permlane32_swap_b32_e32 v80, v81
	v_cvt_pk_bf16_f32 v96, v88, v89
	v_cvt_pk_bf16_f32 v97, v82, v83
	v_lshl_add_u64 v[98:99], v[98:99], 0, v[250:251]
	s_nop 1
	v_permlane16_swap_b32_e32 v100, v102
	v_permlane16_swap_b32_e32 v101, v103
	global_store_dwordx4 v[98:99], v[100:103], off
	s_nop 1
	s_nop 1
	v_permlane16_swap_b32_e32 v94, v96
	v_permlane16_swap_b32_e32 v95, v97
	global_store_dwordx4 v[98:99], v[94:97], off offset:256
	s_nop 1
	s_and_saveexec_b64 s[36:37], vcc
	s_cbranch_execz .LBB0_777
	v_lshlrev_b64 v[82:83], 6, v[196:197]
	v_lshl_add_u64 v[82:83], s[18:19], 0, v[82:83]
	v_lshl_add_u64 v[82:83], s[34:35], 2, v[82:83]
	s_lshl_b32 s12, s48, 2
	v_lshl_add_u64 v[82:83], v[82:83], 0, s[12:13]
	s_waitcnt lgkmcnt(0)
	v_add_f32_e32 v80, v80, v81
	global_store_dword v[82:83], v80, off
; #define PG8_GAS __attribute__((address_space(1)))
; __device__ __forceinline__ unsigned pk2_(float lo, float hi) { f32x2c_t v = {lo, hi}; bf16x2c_t b = __builtin_convertvector(v, bf16x2c_t); return __builtin_bit_cast(unsigned, b); }
;     __device__ __forceinline__ void operator()(const f32x4 (&acc)[2][2][4][2], const Unit& u, int wr, int wc, int fr, int fq) const {
;     ...
;         for (int ai = 0; ai < 2; ++ai)
; #pragma unroll
;             for (int m = 0; m < 4; ++m) {
;                 const int r = row0 + ai * HALF + m * 16; const size_t off = (size_t)r * 1024 + col0; float ss = 0.f;
; #pragma unroll
;                 for (int bj = 0; bj < 2; ++bj)
; #pragma unroll
;                     for (int n = 0; n < 2; ++n) {
;                         const u32x2v w0 = bsv[ai][m][bj][n]; f32x4 bs;
;                         bs[0] = __builtin_bit_cast(float, w0.x << 16); bs[1] = __builtin_bit_cast(float, w0.x & 0xffff0000u); bs[2] = __builtin_bit_cast(float, w0.y << 16); bs[3] = __builtin_bit_cast(float, w0.y & 0xffff0000u);
;                         const f32x4 v = bs + acc[ai][bj][m][n] * alpha;
;                         { u32x2v w; w.x = pk2_(v[0], v[1]); w.y = pk2_(v[2], v[3]); *(PG8_GAS u32x2v*)(hb + off + bj * HALF + n * 16) = w; }
;                         ss += (v[0] * v[0] + v[1] * v[1]) + (v[2] * v[2] + v[3] * v[3]);
;                     }
;                 ss += __shfl_xor(ss, 16); ss += __shfl_xor(ss, 32);
;                 if (fq == 0) ((PG8_GAS float*)parts)[(size_t)r * 16 + u.pn * 4 + wc] = ss;
;             }
.LBB0_777:
	s_or_b64 exec, exec, s[36:37]
	s_waitcnt vmcnt(24)
	v_lshlrev_b32_e32 v80, 16, v198
	s_waitcnt lgkmcnt(0)
	v_and_b32_e32 v81, 0xffff0000, v198
	v_lshlrev_b32_e32 v82, 16, v199
	v_and_b32_e32 v83, 0xffff0000, v199
	v_pk_fma_f32 v[76:77], v[76:77], 0.5, v[80:81] op_sel_hi:[1,0,1]
	v_pk_fma_f32 v[78:79], v[78:79], 0.5, v[82:83] op_sel_hi:[1,0,1]
	v_cvt_pk_bf16_f32 v84, v76, v77
	v_mul_f32_e32 v77, v77, v77
	v_lshl_add_u64 v[82:83], s[16:17], 0, v[194:195]
	v_fmac_f32_e32 v77, v76, v76
	v_mul_f32_e32 v76, v79, v79
	v_cvt_pk_bf16_f32 v85, v78, v79
	v_lshl_add_u64 v[82:83], v[138:139], 1, v[82:83]
	v_fmac_f32_e32 v76, v78, v78
	v_add_f32_e32 v80, v77, v76
	v_lshlrev_b32_e32 v76, 16, v192
	v_and_b32_e32 v77, 0xffff0000, v192
	v_lshlrev_b32_e32 v78, 16, v193
	v_and_b32_e32 v79, 0xffff0000, v193
	v_pk_fma_f32 v[72:73], v[72:73], 0.5, v[76:77] op_sel_hi:[1,0,1]
	v_pk_fma_f32 v[74:75], v[74:75], 0.5, v[78:79] op_sel_hi:[1,0,1]
	v_cvt_pk_bf16_f32 v86, v72, v73
	v_mul_f32_e32 v73, v73, v73
	v_fmac_f32_e32 v73, v72, v72
	v_mul_f32_e32 v72, v75, v75
	v_fmac_f32_e32 v72, v74, v74
	v_add_f32_e32 v72, v73, v72
	v_add_f32_e32 v77, v80, v72
	v_lshlrev_b32_e32 v72, 16, v190
	v_and_b32_e32 v73, 0xffff0000, v190
	v_lshlrev_b32_e32 v78, 16, v191
	v_and_b32_e32 v79, 0xffff0000, v191
	v_pk_fma_f32 v[70:71], v[70:71], 0.5, v[78:79] op_sel_hi:[1,0,1]
	v_pk_fma_f32 v[68:69], v[68:69], 0.5, v[72:73] op_sel_hi:[1,0,1]
	v_mul_f32_e32 v73, v71, v71
	v_mul_f32_e32 v72, v69, v69
	v_fmac_f32_e32 v72, v68, v68
	v_fmac_f32_e32 v73, v70, v70
	v_add_f32_e32 v72, v72, v73
	v_add_f32_e32 v77, v77, v72
	v_lshlrev_b32_e32 v72, 16, v188
	v_and_b32_e32 v73, 0xffff0000, v188
	v_lshlrev_b32_e32 v78, 16, v189
	v_and_b32_e32 v79, 0xffff0000, v189
	v_pk_fma_f32 v[66:67], v[66:67], 0.5, v[78:79] op_sel_hi:[1,0,1]
	v_pk_fma_f32 v[72:73], v[64:65], 0.5, v[72:73] op_sel_hi:[1,0,1]
	v_mul_f32_e32 v65, v67, v67
	v_mul_f32_e32 v64, v73, v73
	v_fmac_f32_e32 v64, v72, v72
	v_fmac_f32_e32 v65, v66, v66
	v_add_f32_e32 v64, v64, v65
	v_add_f32_e32 v64, v77, v64
	v_mov_b32_e32 v65, v64
	s_nop 1
	v_permlane16_swap_b32_e32 v64, v65
	v_cvt_pk_bf16_f32 v78, v68, v69
	v_cvt_pk_bf16_f32 v79, v70, v71
	v_cvt_pk_bf16_f32 v87, v74, v75
	s_waitcnt lgkmcnt(0)
	v_add_f32_e32 v64, v64, v65
	v_mov_b32_e32 v65, v64
	s_nop 1
	v_permlane32_swap_b32_e32 v64, v65
	v_cvt_pk_bf16_f32 v80, v72, v73
	v_cvt_pk_bf16_f32 v81, v66, v67
	v_lshl_add_u64 v[82:83], v[82:83], 0, v[250:251]
	s_nop 1
	v_permlane16_swap_b32_e32 v84, v86
	v_permlane16_swap_b32_e32 v85, v87
	global_store_dwordx4 v[82:83], v[84:87], off
	s_nop 1
	s_nop 1
	v_permlane16_swap_b32_e32 v78, v80
	v_permlane16_swap_b32_e32 v79, v81
	global_store_dwordx4 v[82:83], v[78:81], off offset:256
	s_nop 1
	s_and_saveexec_b64 s[36:37], vcc
	s_cbranch_execz .LBB0_779
	v_lshlrev_b64 v[66:67], 6, v[184:185]
	v_lshl_add_u64 v[66:67], s[18:19], 0, v[66:67]
	v_lshl_add_u64 v[66:67], s[34:35], 2, v[66:67]
	s_lshl_b32 s12, s48, 2
	v_lshl_add_u64 v[66:67], v[66:67], 0, s[12:13]
	s_waitcnt lgkmcnt(0)
	v_add_f32_e32 v64, v64, v65
	global_store_dword v[66:67], v64, off
.LBB0_779:
	s_or_b64 exec, exec, s[36:37]
	s_waitcnt vmcnt(22)
	v_lshlrev_b32_e32 v64, 16, v186
	s_waitcnt lgkmcnt(0)
	v_and_b32_e32 v65, 0xffff0000, v186
	v_lshlrev_b32_e32 v66, 16, v187
	v_and_b32_e32 v67, 0xffff0000, v187
	v_pk_fma_f32 v[60:61], v[60:61], 0.5, v[64:65] op_sel_hi:[1,0,1]
	v_pk_fma_f32 v[62:63], v[62:63], 0.5, v[66:67] op_sel_hi:[1,0,1]
	v_cvt_pk_bf16_f32 v68, v60, v61
	v_mul_f32_e32 v61, v61, v61
	v_lshl_add_u64 v[66:67], s[16:17], 0, v[182:183]
	v_fmac_f32_e32 v61, v60, v60
	v_mul_f32_e32 v60, v63, v63
	v_cvt_pk_bf16_f32 v69, v62, v63
	v_lshl_add_u64 v[66:67], v[138:139], 1, v[66:67]
	v_fmac_f32_e32 v60, v62, v62
	v_add_f32_e32 v64, v61, v60
	v_lshlrev_b32_e32 v60, 16, v180
	v_and_b32_e32 v61, 0xffff0000, v180
	v_lshlrev_b32_e32 v62, 16, v181
	v_and_b32_e32 v63, 0xffff0000, v181
	v_pk_fma_f32 v[56:57], v[56:57], 0.5, v[60:61] op_sel_hi:[1,0,1]
	v_pk_fma_f32 v[58:59], v[58:59], 0.5, v[62:63] op_sel_hi:[1,0,1]
	v_cvt_pk_bf16_f32 v70, v56, v57
	v_mul_f32_e32 v57, v57, v57
	v_fmac_f32_e32 v57, v56, v56
	v_mul_f32_e32 v56, v59, v59
	v_fmac_f32_e32 v56, v58, v58
	v_add_f32_e32 v56, v57, v56
	v_add_f32_e32 v61, v64, v56
	v_lshlrev_b32_e32 v56, 16, v178
	v_and_b32_e32 v57, 0xffff0000, v178
	v_lshlrev_b32_e32 v62, 16, v179
	v_and_b32_e32 v63, 0xffff0000, v179
	v_pk_fma_f32 v[54:55], v[54:55], 0.5, v[62:63] op_sel_hi:[1,0,1]
	v_pk_fma_f32 v[52:53], v[52:53], 0.5, v[56:57] op_sel_hi:[1,0,1]
	v_mul_f32_e32 v57, v55, v55
	v_mul_f32_e32 v56, v53, v53
	v_fmac_f32_e32 v56, v52, v52
	v_fmac_f32_e32 v57, v54, v54
	v_add_f32_e32 v56, v56, v57
	v_add_f32_e32 v61, v61, v56
	v_lshlrev_b32_e32 v56, 16, v176
	v_and_b32_e32 v57, 0xffff0000, v176
	v_lshlrev_b32_e32 v62, 16, v177
	v_and_b32_e32 v63, 0xffff0000, v177
	v_pk_fma_f32 v[50:51], v[50:51], 0.5, v[62:63] op_sel_hi:[1,0,1]
	v_pk_fma_f32 v[56:57], v[48:49], 0.5, v[56:57] op_sel_hi:[1,0,1]
	v_mul_f32_e32 v49, v51, v51
	v_mul_f32_e32 v48, v57, v57
	v_fmac_f32_e32 v48, v56, v56
	v_fmac_f32_e32 v49, v50, v50
	v_add_f32_e32 v48, v48, v49
	v_add_f32_e32 v48, v61, v48
	v_mov_b32_e32 v49, v48
	s_nop 1
	v_permlane16_swap_b32_e32 v48, v49
	v_cvt_pk_bf16_f32 v62, v52, v53
	v_cvt_pk_bf16_f32 v63, v54, v55
	v_cvt_pk_bf16_f32 v71, v58, v59
	s_waitcnt lgkmcnt(0)
	v_add_f32_e32 v48, v48, v49
	v_mov_b32_e32 v49, v48
	s_nop 1
	v_permlane32_swap_b32_e32 v48, v49
	v_cvt_pk_bf16_f32 v64, v56, v57
	v_cvt_pk_bf16_f32 v65, v50, v51
	v_lshl_add_u64 v[66:67], v[66:67], 0, v[250:251]
	s_nop 1
	v_permlane16_swap_b32_e32 v68, v70
	v_permlane16_swap_b32_e32 v69, v71
	global_store_dwordx4 v[66:67], v[68:71], off
	s_nop 1
	s_nop 1
	v_permlane16_swap_b32_e32 v62, v64
	v_permlane16_swap_b32_e32 v63, v65
	global_store_dwordx4 v[66:67], v[62:65], off offset:256
	s_nop 1
	s_and_saveexec_b64 s[36:37], vcc
	s_cbranch_execz .LBB0_781
	v_lshlrev_b64 v[50:51], 6, v[172:173]
	v_lshl_add_u64 v[50:51], s[18:19], 0, v[50:51]
	v_lshl_add_u64 v[50:51], s[34:35], 2, v[50:51]
	s_lshl_b32 s12, s48, 2
	v_lshl_add_u64 v[50:51], v[50:51], 0, s[12:13]
	s_waitcnt lgkmcnt(0)
	v_add_f32_e32 v48, v48, v49
	global_store_dword v[50:51], v48, off
; #define PG8_GAS __attribute__((address_space(1)))
; __device__ __forceinline__ unsigned pk2_(float lo, float hi) { f32x2c_t v = {lo, hi}; bf16x2c_t b = __builtin_convertvector(v, bf16x2c_t); return __builtin_bit_cast(unsigned, b); }
;     __device__ __forceinline__ void operator()(const f32x4 (&acc)[2][2][4][2], const Unit& u, int wr, int wc, int fr, int fq) const {
;     ...
;         for (int ai = 0; ai < 2; ++ai)
; #pragma unroll
;             for (int m = 0; m < 4; ++m) {
;                 const int r = row0 + ai * HALF + m * 16; const size_t off = (size_t)r * 1024 + col0; float ss = 0.f;
; #pragma unroll
;                 for (int bj = 0; bj < 2; ++bj)
; #pragma unroll
;                     for (int n = 0; n < 2; ++n) {
;                         const u32x2v w0 = bsv[ai][m][bj][n]; f32x4 bs;
;                         bs[0] = __builtin_bit_cast(float, w0.x << 16); bs[1] = __builtin_bit_cast(float, w0.x & 0xffff0000u); bs[2] = __builtin_bit_cast(float, w0.y << 16); bs[3] = __builtin_bit_cast(float, w0.y & 0xffff0000u);
;                         const f32x4 v = bs + acc[ai][bj][m][n] * alpha;
;                         { u32x2v w; w.x = pk2_(v[0], v[1]); w.y = pk2_(v[2], v[3]); *(PG8_GAS u32x2v*)(hb + off + bj * HALF + n * 16) = w; }
;                         ss += (v[0] * v[0] + v[1] * v[1]) + (v[2] * v[2] + v[3] * v[3]);
;                     }
;                 ss += __shfl_xor(ss, 16); ss += __shfl_xor(ss, 32);
;                 if (fq == 0) ((PG8_GAS float*)parts)[(size_t)r * 16 + u.pn * 4 + wc] = ss;
;             }
.LBB0_781:
	s_or_b64 exec, exec, s[36:37]
	s_waitcnt vmcnt(20)
	v_lshlrev_b32_e32 v48, 16, v174
	s_waitcnt lgkmcnt(0)
	v_and_b32_e32 v49, 0xffff0000, v174
	v_lshlrev_b32_e32 v50, 16, v175
	v_and_b32_e32 v51, 0xffff0000, v175
	v_pk_fma_f32 v[44:45], v[44:45], 0.5, v[48:49] op_sel_hi:[1,0,1]
	v_pk_fma_f32 v[46:47], v[46:47], 0.5, v[50:51] op_sel_hi:[1,0,1]
	v_cvt_pk_bf16_f32 v52, v44, v45
	v_mul_f32_e32 v45, v45, v45
	v_lshl_add_u64 v[50:51], s[16:17], 0, v[170:171]
	v_fmac_f32_e32 v45, v44, v44
	v_mul_f32_e32 v44, v47, v47
	v_cvt_pk_bf16_f32 v53, v46, v47
	v_lshl_add_u64 v[50:51], v[138:139], 1, v[50:51]
	v_fmac_f32_e32 v44, v46, v46
	v_add_f32_e32 v48, v45, v44
	v_lshlrev_b32_e32 v44, 16, v168
	v_and_b32_e32 v45, 0xffff0000, v168
	v_lshlrev_b32_e32 v46, 16, v169
	v_and_b32_e32 v47, 0xffff0000, v169
	v_pk_fma_f32 v[40:41], v[40:41], 0.5, v[44:45] op_sel_hi:[1,0,1]
	v_pk_fma_f32 v[42:43], v[42:43], 0.5, v[46:47] op_sel_hi:[1,0,1]
	v_cvt_pk_bf16_f32 v54, v40, v41
	v_mul_f32_e32 v41, v41, v41
	v_fmac_f32_e32 v41, v40, v40
	v_mul_f32_e32 v40, v43, v43
	v_fmac_f32_e32 v40, v42, v42
	v_add_f32_e32 v40, v41, v40
	v_add_f32_e32 v45, v48, v40
	v_lshlrev_b32_e32 v40, 16, v166
	v_and_b32_e32 v41, 0xffff0000, v166
	v_lshlrev_b32_e32 v46, 16, v167
	v_and_b32_e32 v47, 0xffff0000, v167
	v_pk_fma_f32 v[38:39], v[38:39], 0.5, v[46:47] op_sel_hi:[1,0,1]
	v_pk_fma_f32 v[36:37], v[36:37], 0.5, v[40:41] op_sel_hi:[1,0,1]
	v_mul_f32_e32 v41, v39, v39
	v_mul_f32_e32 v40, v37, v37
	v_fmac_f32_e32 v40, v36, v36
	v_fmac_f32_e32 v41, v38, v38
	v_add_f32_e32 v40, v40, v41
	v_add_f32_e32 v45, v45, v40
	v_lshlrev_b32_e32 v40, 16, v164
	v_and_b32_e32 v41, 0xffff0000, v164
	v_lshlrev_b32_e32 v46, 16, v165
	v_and_b32_e32 v47, 0xffff0000, v165
	v_pk_fma_f32 v[34:35], v[34:35], 0.5, v[46:47] op_sel_hi:[1,0,1]
	v_pk_fma_f32 v[40:41], v[32:33], 0.5, v[40:41] op_sel_hi:[1,0,1]
	v_mul_f32_e32 v33, v35, v35
	v_mul_f32_e32 v32, v41, v41
	v_fmac_f32_e32 v32, v40, v40
	v_fmac_f32_e32 v33, v34, v34
	v_add_f32_e32 v32, v32, v33
	v_add_f32_e32 v32, v45, v32
	v_mov_b32_e32 v33, v32
	s_nop 1
	v_permlane16_swap_b32_e32 v32, v33
	v_cvt_pk_bf16_f32 v46, v36, v37
	v_cvt_pk_bf16_f32 v47, v38, v39
	v_cvt_pk_bf16_f32 v55, v42, v43
	s_waitcnt lgkmcnt(0)
	v_add_f32_e32 v32, v32, v33
	v_mov_b32_e32 v33, v32
	s_nop 1
	v_permlane32_swap_b32_e32 v32, v33
	v_cvt_pk_bf16_f32 v48, v40, v41
	v_cvt_pk_bf16_f32 v49, v34, v35
	v_lshl_add_u64 v[50:51], v[50:51], 0, v[250:251]
	s_nop 1
	v_permlane16_swap_b32_e32 v52, v54
	v_permlane16_swap_b32_e32 v53, v55
	global_store_dwordx4 v[50:51], v[52:55], off
	s_nop 1
	s_nop 1
	v_permlane16_swap_b32_e32 v46, v48
	v_permlane16_swap_b32_e32 v47, v49
	global_store_dwordx4 v[50:51], v[46:49], off offset:256
	s_nop 1
	s_and_saveexec_b64 s[36:37], vcc
	s_cbranch_execz .LBB0_783
	v_lshlrev_b64 v[34:35], 6, v[160:161]
	v_lshl_add_u64 v[34:35], s[18:19], 0, v[34:35]
	v_lshl_add_u64 v[34:35], s[34:35], 2, v[34:35]
	s_lshl_b32 s12, s48, 2
	v_lshl_add_u64 v[34:35], v[34:35], 0, s[12:13]
	s_waitcnt lgkmcnt(0)
	v_add_f32_e32 v32, v32, v33
	global_store_dword v[34:35], v32, off
; #define PG8_GAS __attribute__((address_space(1)))
; __device__ __forceinline__ unsigned pk2_(float lo, float hi) { f32x2c_t v = {lo, hi}; bf16x2c_t b = __builtin_convertvector(v, bf16x2c_t); return __builtin_bit_cast(unsigned, b); }
;     __device__ __forceinline__ void operator()(const f32x4 (&acc)[2][2][4][2], const Unit& u, int wr, int wc, int fr, int fq) const {
;     ...
;         for (int ai = 0; ai < 2; ++ai)
; #pragma unroll
;             for (int m = 0; m < 4; ++m) {
;                 const int r = row0 + ai * HALF + m * 16; const size_t off = (size_t)r * 1024 + col0; float ss = 0.f;
; #pragma unroll
;                 for (int bj = 0; bj < 2; ++bj)
; #pragma unroll
;                     for (int n = 0; n < 2; ++n) {
;                         const u32x2v w0 = bsv[ai][m][bj][n]; f32x4 bs;
;                         bs[0] = __builtin_bit_cast(float, w0.x << 16); bs[1] = __builtin_bit_cast(float, w0.x & 0xffff0000u); bs[2] = __builtin_bit_cast(float, w0.y << 16); bs[3] = __builtin_bit_cast(float, w0.y & 0xffff0000u);
;                         const f32x4 v = bs + acc[ai][bj][m][n] * alpha;
;                         { u32x2v w; w.x = pk2_(v[0], v[1]); w.y = pk2_(v[2], v[3]); *(PG8_GAS u32x2v*)(hb + off + bj * HALF + n * 16) = w; }
;                         ss += (v[0] * v[0] + v[1] * v[1]) + (v[2] * v[2] + v[3] * v[3]);
;                     }
;                 ss += __shfl_xor(ss, 16); ss += __shfl_xor(ss, 32);
;                 if (fq == 0) ((PG8_GAS float*)parts)[(size_t)r * 16 + u.pn * 4 + wc] = ss;
;             }
.LBB0_783:
	s_or_b64 exec, exec, s[36:37]
	s_waitcnt vmcnt(18)
	v_lshlrev_b32_e32 v32, 16, v162
	s_waitcnt lgkmcnt(0)
	v_and_b32_e32 v33, 0xffff0000, v162
	v_lshlrev_b32_e32 v34, 16, v163
	v_and_b32_e32 v35, 0xffff0000, v163
	v_pk_fma_f32 v[28:29], v[28:29], 0.5, v[32:33] op_sel_hi:[1,0,1]
	v_pk_fma_f32 v[30:31], v[30:31], 0.5, v[34:35] op_sel_hi:[1,0,1]
	v_cvt_pk_bf16_f32 v36, v28, v29
	v_mul_f32_e32 v29, v29, v29
	v_lshl_add_u64 v[34:35], s[16:17], 0, v[158:159]
	v_fmac_f32_e32 v29, v28, v28
	v_mul_f32_e32 v28, v31, v31
	v_cvt_pk_bf16_f32 v37, v30, v31
	v_lshl_add_u64 v[34:35], v[138:139], 1, v[34:35]
	v_fmac_f32_e32 v28, v30, v30
	v_add_f32_e32 v32, v29, v28
	v_lshlrev_b32_e32 v28, 16, v156
	v_and_b32_e32 v29, 0xffff0000, v156
	v_lshlrev_b32_e32 v30, 16, v157
	v_and_b32_e32 v31, 0xffff0000, v157
	v_pk_fma_f32 v[24:25], v[24:25], 0.5, v[28:29] op_sel_hi:[1,0,1]
	v_pk_fma_f32 v[26:27], v[26:27], 0.5, v[30:31] op_sel_hi:[1,0,1]
	v_cvt_pk_bf16_f32 v38, v24, v25
	v_mul_f32_e32 v25, v25, v25
	v_fmac_f32_e32 v25, v24, v24
	v_mul_f32_e32 v24, v27, v27
	v_fmac_f32_e32 v24, v26, v26
	v_add_f32_e32 v24, v25, v24
	v_add_f32_e32 v29, v32, v24
	v_lshlrev_b32_e32 v24, 16, v154
	v_and_b32_e32 v25, 0xffff0000, v154
	v_lshlrev_b32_e32 v30, 16, v155
	v_and_b32_e32 v31, 0xffff0000, v155
	v_pk_fma_f32 v[22:23], v[22:23], 0.5, v[30:31] op_sel_hi:[1,0,1]
	v_pk_fma_f32 v[20:21], v[20:21], 0.5, v[24:25] op_sel_hi:[1,0,1]
	v_mul_f32_e32 v25, v23, v23
	v_mul_f32_e32 v24, v21, v21
	v_fmac_f32_e32 v24, v20, v20
	v_fmac_f32_e32 v25, v22, v22
	v_add_f32_e32 v24, v24, v25
	v_add_f32_e32 v29, v29, v24
	v_lshlrev_b32_e32 v24, 16, v152
	v_and_b32_e32 v25, 0xffff0000, v152
	v_lshlrev_b32_e32 v30, 16, v153
	v_and_b32_e32 v31, 0xffff0000, v153
	v_pk_fma_f32 v[18:19], v[18:19], 0.5, v[30:31] op_sel_hi:[1,0,1]
	v_pk_fma_f32 v[24:25], v[16:17], 0.5, v[24:25] op_sel_hi:[1,0,1]
	v_mul_f32_e32 v17, v19, v19
	v_mul_f32_e32 v16, v25, v25
	v_fmac_f32_e32 v16, v24, v24
	v_fmac_f32_e32 v17, v18, v18
	v_add_f32_e32 v16, v16, v17
	v_add_f32_e32 v16, v29, v16
	v_mov_b32_e32 v17, v16
	s_nop 1
	v_permlane16_swap_b32_e32 v16, v17
	v_cvt_pk_bf16_f32 v30, v20, v21
	v_cvt_pk_bf16_f32 v31, v22, v23
	v_cvt_pk_bf16_f32 v39, v26, v27
	s_waitcnt lgkmcnt(0)
	v_add_f32_e32 v16, v16, v17
	v_mov_b32_e32 v17, v16
	s_nop 1
	v_permlane32_swap_b32_e32 v16, v17
	v_cvt_pk_bf16_f32 v32, v24, v25
	v_cvt_pk_bf16_f32 v33, v18, v19
	v_lshl_add_u64 v[34:35], v[34:35], 0, v[250:251]
	s_nop 1
	v_permlane16_swap_b32_e32 v36, v38
	v_permlane16_swap_b32_e32 v37, v39
	global_store_dwordx4 v[34:35], v[36:39], off
	s_nop 1
	s_nop 1
	v_permlane16_swap_b32_e32 v30, v32
	v_permlane16_swap_b32_e32 v31, v33
	global_store_dwordx4 v[34:35], v[30:33], off offset:256
	s_nop 1
	s_and_saveexec_b64 s[36:37], vcc
	s_cbranch_execz .LBB0_785
	v_lshlrev_b64 v[18:19], 6, v[148:149]
	v_lshl_add_u64 v[18:19], s[18:19], 0, v[18:19]
	v_lshl_add_u64 v[18:19], s[34:35], 2, v[18:19]
	s_lshl_b32 s12, s48, 2
	v_lshl_add_u64 v[18:19], v[18:19], 0, s[12:13]
	s_waitcnt lgkmcnt(0)
	v_add_f32_e32 v16, v16, v17
	global_store_dword v[18:19], v16, off
.LBB0_785:
	s_or_b64 exec, exec, s[36:37]
	s_waitcnt vmcnt(16)
	v_lshlrev_b32_e32 v16, 16, v150
	s_waitcnt lgkmcnt(0)
	v_and_b32_e32 v17, 0xffff0000, v150
	v_lshlrev_b32_e32 v18, 16, v151
	v_and_b32_e32 v19, 0xffff0000, v151
	v_pk_fma_f32 v[12:13], v[12:13], 0.5, v[16:17] op_sel_hi:[1,0,1]
	v_pk_fma_f32 v[14:15], v[14:15], 0.5, v[18:19] op_sel_hi:[1,0,1]
	v_cvt_pk_bf16_f32 v20, v12, v13
	v_mul_f32_e32 v13, v13, v13
	v_lshl_add_u64 v[18:19], s[16:17], 0, v[146:147]
	v_fmac_f32_e32 v13, v12, v12
	v_mul_f32_e32 v12, v15, v15
	v_cvt_pk_bf16_f32 v21, v14, v15
	v_lshl_add_u64 v[18:19], v[138:139], 1, v[18:19]
	v_fmac_f32_e32 v12, v14, v14
	v_add_f32_e32 v16, v13, v12
	v_lshlrev_b32_e32 v12, 16, v144
	v_and_b32_e32 v13, 0xffff0000, v144
	v_lshlrev_b32_e32 v14, 16, v145
	v_and_b32_e32 v15, 0xffff0000, v145
	v_pk_fma_f32 v[8:9], v[8:9], 0.5, v[12:13] op_sel_hi:[1,0,1]
	v_pk_fma_f32 v[10:11], v[10:11], 0.5, v[14:15] op_sel_hi:[1,0,1]
	v_cvt_pk_bf16_f32 v22, v8, v9
	v_mul_f32_e32 v9, v9, v9
	v_fmac_f32_e32 v9, v8, v8
	v_mul_f32_e32 v8, v11, v11
	v_fmac_f32_e32 v8, v10, v10
	v_add_f32_e32 v8, v9, v8
	v_add_f32_e32 v13, v16, v8
	v_lshlrev_b32_e32 v8, 16, v142
	v_and_b32_e32 v9, 0xffff0000, v142
	v_lshlrev_b32_e32 v14, 16, v143
	v_and_b32_e32 v15, 0xffff0000, v143
	v_pk_fma_f32 v[6:7], v[6:7], 0.5, v[14:15] op_sel_hi:[1,0,1]
	v_pk_fma_f32 v[4:5], v[4:5], 0.5, v[8:9] op_sel_hi:[1,0,1]
	v_mul_f32_e32 v9, v7, v7
	v_mul_f32_e32 v8, v5, v5
	v_fmac_f32_e32 v8, v4, v4
	v_fmac_f32_e32 v9, v6, v6
	v_add_f32_e32 v8, v8, v9
	v_add_f32_e32 v13, v13, v8
	v_lshlrev_b32_e32 v8, 16, v140
	v_and_b32_e32 v9, 0xffff0000, v140
	v_lshlrev_b32_e32 v14, 16, v141
	v_and_b32_e32 v15, 0xffff0000, v141
	v_pk_fma_f32 v[2:3], v[2:3], 0.5, v[14:15] op_sel_hi:[1,0,1]
	v_pk_fma_f32 v[8:9], v[0:1], 0.5, v[8:9] op_sel_hi:[1,0,1]
	v_mul_f32_e32 v1, v3, v3
	v_mul_f32_e32 v0, v9, v9
	v_fmac_f32_e32 v0, v8, v8
	v_fmac_f32_e32 v1, v2, v2
	v_add_f32_e32 v0, v0, v1
	v_add_f32_e32 v0, v13, v0
	v_mov_b32_e32 v1, v0
	s_nop 1
	v_permlane16_swap_b32_e32 v0, v1
	v_cvt_pk_bf16_f32 v14, v4, v5
	v_cvt_pk_bf16_f32 v15, v6, v7
	v_cvt_pk_bf16_f32 v23, v10, v11
	s_waitcnt lgkmcnt(0)
	v_add_f32_e32 v0, v0, v1
	v_mov_b32_e32 v1, v0
	s_nop 1
	v_permlane32_swap_b32_e32 v0, v1
	v_cvt_pk_bf16_f32 v16, v8, v9
	v_cvt_pk_bf16_f32 v17, v2, v3
	v_lshl_add_u64 v[18:19], v[18:19], 0, v[250:251]
	s_nop 1
	v_permlane16_swap_b32_e32 v20, v22
	v_permlane16_swap_b32_e32 v21, v23
	global_store_dwordx4 v[18:19], v[20:23], off
	s_nop 1
	s_nop 1
	v_permlane16_swap_b32_e32 v14, v16
	v_permlane16_swap_b32_e32 v15, v17
	global_store_dwordx4 v[18:19], v[14:17], off offset:256
	s_nop 1
	s_and_saveexec_b64 s[36:37], vcc
	s_cbranch_execz .LBB0_787
	v_lshlrev_b64 v[2:3], 6, v[136:137]
	v_lshl_add_u64 v[2:3], s[18:19], 0, v[2:3]
	v_lshl_add_u64 v[2:3], s[34:35], 2, v[2:3]
	s_lshl_b32 s12, s48, 2
	v_lshl_add_u64 v[2:3], v[2:3], 0, s[12:13]
	s_waitcnt lgkmcnt(0)
	v_add_f32_e32 v0, v0, v1
	global_store_dword v[2:3], v0, off

; #define PG8_GAS __attribute__((address_space(1)))
; __device__ __forceinline__ unsigned pk2_(float lo, float hi) { f32x2c_t v = {lo, hi}; bf16x2c_t b = __builtin_convertvector(v, bf16x2c_t); return __builtin_bit_cast(unsigned, b); }
;     __device__ __forceinline__ void operator()(const f32x4 (&acc)[2][2][4][2], const Unit& u, int wr, int wc, int fr, int fq) const {
;         typedef unsigned u32x2v __attribute__((ext_vector_type(2)));
;         const int row0 = u.pm * BM + wr * 64 + fr, col0 = u.pn * BM + wc * 32 + 4 * fq;
;         u32x2v bsv[2][4][2][2];
; #pragma unroll
;         for (int ai = 0; ai < 2; ++ai)
; #pragma unroll
;             for (int m = 0; m < 4; ++m) { const size_t off = (size_t)(row0 + ai * HALF + m * 16) * 1024 + col0;
; #pragma unroll
;                 for (int bj = 0; bj < 2; ++bj)
; #pragma unroll
;                     for (int n = 0; n < 2; ++n) bsv[ai][m][bj][n] = *(const PG8_GAS u32x2v*)(hbase + off + bj * HALF + n * 16); }
; #pragma unroll
;         for (int ai = 0; ai < 2; ++ai)
; #pragma unroll
;             for (int m = 0; m < 4; ++m) {
;                 const int r = row0 + ai * HALF + m * 16; const size_t off = (size_t)r * 1024 + col0; float ss = 0.f;
; #pragma unroll
;                 for (int bj = 0; bj < 2; ++bj)
; #pragma unroll
;                     for (int n = 0; n < 2; ++n) {
;                         const u32x2v w0 = bsv[ai][m][bj][n]; f32x4 bs;
;                         bs[0] = __builtin_bit_cast(float, w0.x << 16); bs[1] = __builtin_bit_cast(float, w0.x & 0xffff0000u); bs[2] = __builtin_bit_cast(float, w0.y << 16); bs[3] = __builtin_bit_cast(float, w0.y & 0xffff0000u);
;                         const f32x4 v = bs + acc[ai][bj][m][n] * alpha;
;                         { u32x2v w; w.x = pk2_(v[0], v[1]); w.y = pk2_(v[2], v[3]); *(PG8_GAS u32x2v*)(hb + off + bj * HALF + n * 16) = w; }
;                         ss += (v[0] * v[0] + v[1] * v[1]) + (v[2] * v[2] + v[3] * v[3]);
;                     }
;                 ss += __shfl_xor(ss, 16); ss += __shfl_xor(ss, 32);
;                 if (fq == 0) ((PG8_GAS float*)parts)[(size_t)r * 16 + u.pn * 4 + wc] = ss;
;             }
;     }
.LBB0_1378:
	s_lshl_b32 s27, s36, 8
	v_mov_b32_e32 v136, v252
	s_add_i32 s27, s27, s54
	v_cmp_lt_i32_e32 vcc, v227, v226
	v_and_or_b32 v220, v136, 15, s27
	s_lshl_b32 s27, s10, 8
	v_bfe_u32 v244, v136, 4, 2
	s_or_b32 s27, s27, s55
	v_lshl_or_b32 v138, v244, 2, s27
	v_ashrrev_i32_e32 v139, 31, v138
	v_lshlrev_b64 v[224:225], 1, v[138:139]
	v_ashrrev_i32_e32 v221, 31, v220
	v_lshl_add_u64 v[140:141], s[12:13], 0, v[224:225]
	v_lshlrev_b64 v[234:235], 11, v[220:221]
	v_lshl_add_u64 v[136:137], v[140:141], 0, v[234:235]
	global_load_dwordx2 v[236:237], v[136:137], off
	global_load_dwordx2 v[238:239], v[136:137], off offset:32
	global_load_dwordx2 v[240:241], v[136:137], off offset:256
	global_load_dwordx2 v[242:243], v[136:137], off offset:288
	v_or_b32_e32 v208, 16, v220
	v_ashrrev_i32_e32 v209, 31, v208
	v_or_b32_e32 v196, 32, v220
	v_lshlrev_b64 v[218:219], 11, v[208:209]
	v_ashrrev_i32_e32 v197, 31, v196
	v_or_b32_e32 v184, 48, v220
	v_lshl_add_u64 v[136:137], v[140:141], 0, v[218:219]
	v_lshlrev_b64 v[206:207], 11, v[196:197]
	v_ashrrev_i32_e32 v185, 31, v184
	v_add_u32_e32 v172, 0x80, v220
	global_load_dwordx2 v[222:223], v[136:137], off
	global_load_dwordx2 v[216:217], v[136:137], off offset:32
	global_load_dwordx2 v[214:215], v[136:137], off offset:256
	global_load_dwordx2 v[212:213], v[136:137], off offset:288
	v_lshl_add_u64 v[136:137], v[140:141], 0, v[206:207]
	v_lshlrev_b64 v[194:195], 11, v[184:185]
	v_ashrrev_i32_e32 v173, 31, v172
	v_add_u32_e32 v160, 0x90, v220
	global_load_dwordx2 v[210:211], v[136:137], off
	global_load_dwordx2 v[204:205], v[136:137], off offset:32
	global_load_dwordx2 v[202:203], v[136:137], off offset:256
	global_load_dwordx2 v[200:201], v[136:137], off offset:288
	v_lshl_add_u64 v[136:137], v[140:141], 0, v[194:195]
	v_lshlrev_b64 v[182:183], 11, v[172:173]
	v_ashrrev_i32_e32 v161, 31, v160
	v_add_u32_e32 v148, 0xa0, v220
	global_load_dwordx2 v[198:199], v[136:137], off
	global_load_dwordx2 v[192:193], v[136:137], off offset:32
	global_load_dwordx2 v[190:191], v[136:137], off offset:256
	global_load_dwordx2 v[188:189], v[136:137], off offset:288
	v_lshl_add_u64 v[136:137], v[140:141], 0, v[182:183]
	v_lshlrev_b64 v[170:171], 11, v[160:161]
	v_ashrrev_i32_e32 v149, 31, v148
	global_load_dwordx2 v[186:187], v[136:137], off
	global_load_dwordx2 v[180:181], v[136:137], off offset:32
	global_load_dwordx2 v[178:179], v[136:137], off offset:256
	global_load_dwordx2 v[176:177], v[136:137], off offset:288
	v_lshl_add_u64 v[136:137], v[140:141], 0, v[170:171]
	v_lshlrev_b64 v[158:159], 11, v[148:149]
	global_load_dwordx2 v[174:175], v[136:137], off
	global_load_dwordx2 v[168:169], v[136:137], off offset:32
	global_load_dwordx2 v[166:167], v[136:137], off offset:256
	global_load_dwordx2 v[164:165], v[136:137], off offset:288
	v_lshl_add_u64 v[136:137], v[140:141], 0, v[158:159]
	global_load_dwordx2 v[162:163], v[136:137], off
	global_load_dwordx2 v[156:157], v[136:137], off offset:32
	global_load_dwordx2 v[154:155], v[136:137], off offset:256
	global_load_dwordx2 v[152:153], v[136:137], off offset:288
	v_add_u32_e32 v136, 0xb0, v220
	v_ashrrev_i32_e32 v137, 31, v136
	v_lshlrev_b64 v[146:147], 11, v[136:137]
	v_lshl_add_u64 v[140:141], v[140:141], 0, v[146:147]
	global_load_dwordx2 v[150:151], v[140:141], off
	global_load_dwordx2 v[144:145], v[140:141], off offset:32
	global_load_dwordx2 v[142:143], v[140:141], off offset:256
	s_nop 0
	global_load_dwordx2 v[140:141], v[140:141], off offset:288
	v_bfe_u32 v250, v252, 4, 1
	v_mul_u32_u24_e32 v250, 24, v250
	v_mov_b32_e32 v251, 0
	v_xor_b32_e32 v245, 32, v253
	v_cndmask_b32_e32 v232, v253, v227, vcc
	v_cmp_lt_i32_e32 vcc, v245, v226
	v_lshlrev_b32_e32 v233, 2, v232
	v_lshl_add_u64 v[234:235], s[12:13], 0, v[234:235]
	v_cndmask_b32_e32 v232, v253, v245, vcc
	v_cmp_eq_u32_e32 vcc, 0, v244
	v_lshl_add_u64 v[224:225], v[234:235], 0, v[224:225]
	v_lshlrev_b32_e32 v232, 2, v232
	s_lshl_b32 s36, s10, 2
	s_ashr_i32 s37, s36, 31
	s_waitcnt vmcnt(28)
	v_lshlrev_b32_e32 v244, 16, v236
	v_and_b32_e32 v245, 0xffff0000, v236
	v_lshlrev_b32_e32 v236, 16, v237
	v_and_b32_e32 v237, 0xffff0000, v237
	v_pk_add_f32 v[124:125], v[124:125], v[244:245]
	v_pk_add_f32 v[126:127], v[126:127], v[236:237]
	v_cvt_pk_bf16_f32 v236, v124, v125
	v_mul_f32_e32 v125, v125, v125
	v_fmac_f32_e32 v125, v124, v124
	v_mul_f32_e32 v124, v127, v127
	v_fmac_f32_e32 v124, v126, v126
	v_add_f32_e32 v234, v125, v124
	v_lshlrev_b32_e32 v124, 16, v238
	v_and_b32_e32 v125, 0xffff0000, v238
	v_cvt_pk_bf16_f32 v237, v126, v127
	v_lshlrev_b32_e32 v126, 16, v239
	v_and_b32_e32 v127, 0xffff0000, v239
	v_pk_add_f32 v[120:121], v[120:121], v[124:125]
	v_pk_add_f32 v[122:123], v[122:123], v[126:127]
	v_cvt_pk_bf16_f32 v124, v120, v121
	v_mul_f32_e32 v121, v121, v121
	v_fmac_f32_e32 v121, v120, v120
	v_mul_f32_e32 v120, v123, v123
	v_fmac_f32_e32 v120, v122, v122
	v_add_f32_e32 v120, v121, v120
	v_add_f32_e32 v125, v234, v120
	v_lshlrev_b32_e32 v120, 16, v240
	v_and_b32_e32 v121, 0xffff0000, v240
	v_lshlrev_b32_e32 v126, 16, v241
	v_and_b32_e32 v127, 0xffff0000, v241
	v_pk_add_f32 v[118:119], v[118:119], v[126:127]
	v_pk_add_f32 v[116:117], v[116:117], v[120:121]
	v_mul_f32_e32 v121, v119, v119
	v_mul_f32_e32 v120, v117, v117
	v_fmac_f32_e32 v120, v116, v116
	v_fmac_f32_e32 v121, v118, v118
	v_add_f32_e32 v120, v120, v121
	v_add_f32_e32 v125, v125, v120
	v_lshlrev_b32_e32 v120, 16, v242
	v_and_b32_e32 v121, 0xffff0000, v242
	v_lshlrev_b32_e32 v126, 16, v243
	v_and_b32_e32 v127, 0xffff0000, v243
	v_pk_add_f32 v[114:115], v[114:115], v[126:127]
	v_pk_add_f32 v[120:121], v[112:113], v[120:121]
	v_mul_f32_e32 v113, v115, v115
	v_mul_f32_e32 v112, v121, v121
	v_fmac_f32_e32 v112, v120, v120
	v_fmac_f32_e32 v113, v114, v114
	v_add_f32_e32 v112, v112, v113
	v_add_f32_e32 v112, v125, v112
	v_mov_b32_e32 v113, v112
	s_nop 1
	v_permlane16_swap_b32_e32 v112, v113
	v_cvt_pk_bf16_f32 v116, v116, v117
	v_cvt_pk_bf16_f32 v117, v118, v119
	v_cvt_pk_bf16_f32 v125, v122, v123
	global_store_dwordx2 v[224:225], v[116:117], off offset:256
	s_waitcnt lgkmcnt(0)
	v_add_f32_e32 v112, v112, v113
	v_mov_b32_e32 v113, v112
	s_nop 1
	v_permlane32_swap_b32_e32 v112, v113
	v_cvt_pk_bf16_f32 v116, v120, v121
	v_cvt_pk_bf16_f32 v117, v114, v115
	global_store_dwordx2 v[224:225], v[236:237], off
	global_store_dwordx2 v[224:225], v[124:125], off offset:32
	global_store_dwordx2 v[224:225], v[116:117], off offset:288
	s_and_saveexec_b64 s[38:39], vcc
	s_cbranch_execz .LBB0_1380
	v_lshlrev_b64 v[114:115], 6, v[220:221]
	v_lshl_add_u64 v[114:115], s[14:15], 0, v[114:115]
	v_lshl_add_u64 v[114:115], s[36:37], 2, v[114:115]
	s_lshl_b32 s10, s53, 2
	v_lshl_add_u64 v[114:115], v[114:115], 0, s[10:11]
	s_waitcnt lgkmcnt(0)
	v_add_f32_e32 v112, v112, v113
	global_store_dword v[114:115], v112, off
; #define PG8_GAS __attribute__((address_space(1)))
; __device__ __forceinline__ unsigned pk2_(float lo, float hi) { f32x2c_t v = {lo, hi}; bf16x2c_t b = __builtin_convertvector(v, bf16x2c_t); return __builtin_bit_cast(unsigned, b); }
;     __device__ __forceinline__ void operator()(const f32x4 (&acc)[2][2][4][2], const Unit& u, int wr, int wc, int fr, int fq) const {
;     ...
;         for (int ai = 0; ai < 2; ++ai)
; #pragma unroll
;             for (int m = 0; m < 4; ++m) {
;                 const int r = row0 + ai * HALF + m * 16; const size_t off = (size_t)r * 1024 + col0; float ss = 0.f;
; #pragma unroll
;                 for (int bj = 0; bj < 2; ++bj)
; #pragma unroll
;                     for (int n = 0; n < 2; ++n) {
;                         const u32x2v w0 = bsv[ai][m][bj][n]; f32x4 bs;
;                         bs[0] = __builtin_bit_cast(float, w0.x << 16); bs[1] = __builtin_bit_cast(float, w0.x & 0xffff0000u); bs[2] = __builtin_bit_cast(float, w0.y << 16); bs[3] = __builtin_bit_cast(float, w0.y & 0xffff0000u);
;                         const f32x4 v = bs + acc[ai][bj][m][n] * alpha;
;                         { u32x2v w; w.x = pk2_(v[0], v[1]); w.y = pk2_(v[2], v[3]); *(PG8_GAS u32x2v*)(hb + off + bj * HALF + n * 16) = w; }
;                         ss += (v[0] * v[0] + v[1] * v[1]) + (v[2] * v[2] + v[3] * v[3]);
;                     }
;                 ss += __shfl_xor(ss, 16); ss += __shfl_xor(ss, 32);
;                 if (fq == 0) ((PG8_GAS float*)parts)[(size_t)r * 16 + u.pn * 4 + wc] = ss;
;             }
.LBB0_1380:
	s_or_b64 exec, exec, s[38:39]
	s_waitcnt vmcnt(28)
	v_lshlrev_b32_e32 v112, 16, v222
	s_waitcnt lgkmcnt(0)
	v_and_b32_e32 v113, 0xffff0000, v222
	v_lshlrev_b32_e32 v114, 16, v223
	v_and_b32_e32 v115, 0xffff0000, v223
	v_pk_add_f32 v[108:109], v[108:109], v[112:113]
	v_pk_add_f32 v[110:111], v[110:111], v[114:115]
	v_cvt_pk_bf16_f32 v116, v108, v109
	v_mul_f32_e32 v109, v109, v109
	v_lshl_add_u64 v[114:115], s[12:13], 0, v[218:219]
	v_fmac_f32_e32 v109, v108, v108
	v_mul_f32_e32 v108, v111, v111
	v_cvt_pk_bf16_f32 v117, v110, v111
	v_lshl_add_u64 v[114:115], v[138:139], 1, v[114:115]
	v_fmac_f32_e32 v108, v110, v110
	v_add_f32_e32 v112, v109, v108
	v_lshlrev_b32_e32 v108, 16, v216
	v_and_b32_e32 v109, 0xffff0000, v216
	v_lshlrev_b32_e32 v110, 16, v217
	v_and_b32_e32 v111, 0xffff0000, v217
	v_pk_add_f32 v[104:105], v[104:105], v[108:109]
	v_pk_add_f32 v[106:107], v[106:107], v[110:111]
	v_cvt_pk_bf16_f32 v118, v104, v105
	v_mul_f32_e32 v105, v105, v105
	v_fmac_f32_e32 v105, v104, v104
	v_mul_f32_e32 v104, v107, v107
	v_fmac_f32_e32 v104, v106, v106
	v_add_f32_e32 v104, v105, v104
	v_add_f32_e32 v109, v112, v104
	v_lshlrev_b32_e32 v104, 16, v214
	v_and_b32_e32 v105, 0xffff0000, v214
	v_lshlrev_b32_e32 v110, 16, v215
	v_and_b32_e32 v111, 0xffff0000, v215
	v_pk_add_f32 v[102:103], v[102:103], v[110:111]
	v_pk_add_f32 v[100:101], v[100:101], v[104:105]
	v_mul_f32_e32 v105, v103, v103
	v_mul_f32_e32 v104, v101, v101
	v_fmac_f32_e32 v104, v100, v100
	v_fmac_f32_e32 v105, v102, v102
	v_add_f32_e32 v104, v104, v105
	v_add_f32_e32 v109, v109, v104
	v_lshlrev_b32_e32 v104, 16, v212
	v_and_b32_e32 v105, 0xffff0000, v212
	v_lshlrev_b32_e32 v110, 16, v213
	v_and_b32_e32 v111, 0xffff0000, v213
	v_pk_add_f32 v[98:99], v[98:99], v[110:111]
	v_pk_add_f32 v[104:105], v[96:97], v[104:105]
	v_mul_f32_e32 v97, v99, v99
	v_mul_f32_e32 v96, v105, v105
	v_fmac_f32_e32 v96, v104, v104
	v_fmac_f32_e32 v97, v98, v98
	v_add_f32_e32 v96, v96, v97
	v_add_f32_e32 v96, v109, v96
	v_mov_b32_e32 v97, v96
	s_nop 1
	v_permlane16_swap_b32_e32 v96, v97
	v_cvt_pk_bf16_f32 v110, v100, v101
	v_cvt_pk_bf16_f32 v111, v102, v103
	v_cvt_pk_bf16_f32 v119, v106, v107
	s_waitcnt lgkmcnt(0)
	v_add_f32_e32 v96, v96, v97
	v_mov_b32_e32 v97, v96
	s_nop 1
	v_permlane32_swap_b32_e32 v96, v97
	v_cvt_pk_bf16_f32 v112, v104, v105
	v_cvt_pk_bf16_f32 v113, v98, v99
	v_lshl_add_u64 v[114:115], v[114:115], 0, v[250:251]
	s_nop 1
	v_permlane16_swap_b32_e32 v116, v118
	v_permlane16_swap_b32_e32 v117, v119
	global_store_dwordx4 v[114:115], v[116:119], off
	s_nop 1
	s_nop 1
	v_permlane16_swap_b32_e32 v110, v112
	v_permlane16_swap_b32_e32 v111, v113
	global_store_dwordx4 v[114:115], v[110:113], off offset:256
	s_nop 1
	s_and_saveexec_b64 s[38:39], vcc
	s_cbranch_execz .LBB0_1382
	v_lshlrev_b64 v[98:99], 6, v[208:209]
	v_lshl_add_u64 v[98:99], s[14:15], 0, v[98:99]
	v_lshl_add_u64 v[98:99], s[36:37], 2, v[98:99]
	s_lshl_b32 s10, s53, 2
	v_lshl_add_u64 v[98:99], v[98:99], 0, s[10:11]
	s_waitcnt lgkmcnt(0)
	v_add_f32_e32 v96, v96, v97
	global_store_dword v[98:99], v96, off
.LBB0_1382:
	s_or_b64 exec, exec, s[38:39]
	s_waitcnt vmcnt(26)
	v_lshlrev_b32_e32 v96, 16, v210
	s_waitcnt lgkmcnt(0)
	v_and_b32_e32 v97, 0xffff0000, v210
	v_lshlrev_b32_e32 v98, 16, v211
	v_and_b32_e32 v99, 0xffff0000, v211
	v_pk_add_f32 v[92:93], v[92:93], v[96:97]
	v_pk_add_f32 v[94:95], v[94:95], v[98:99]
	v_cvt_pk_bf16_f32 v100, v92, v93
	v_mul_f32_e32 v93, v93, v93
	v_lshl_add_u64 v[98:99], s[12:13], 0, v[206:207]
	v_fmac_f32_e32 v93, v92, v92
	v_mul_f32_e32 v92, v95, v95
	v_cvt_pk_bf16_f32 v101, v94, v95
	v_lshl_add_u64 v[98:99], v[138:139], 1, v[98:99]
	v_fmac_f32_e32 v92, v94, v94
	v_add_f32_e32 v96, v93, v92
	v_lshlrev_b32_e32 v92, 16, v204
	v_and_b32_e32 v93, 0xffff0000, v204
	v_lshlrev_b32_e32 v94, 16, v205
	v_and_b32_e32 v95, 0xffff0000, v205
	v_pk_add_f32 v[88:89], v[88:89], v[92:93]
	v_pk_add_f32 v[90:91], v[90:91], v[94:95]
	v_cvt_pk_bf16_f32 v102, v88, v89
	v_mul_f32_e32 v89, v89, v89
	v_fmac_f32_e32 v89, v88, v88
	v_mul_f32_e32 v88, v91, v91
	v_fmac_f32_e32 v88, v90, v90
	v_add_f32_e32 v88, v89, v88
	v_add_f32_e32 v93, v96, v88
	v_lshlrev_b32_e32 v88, 16, v202
	v_and_b32_e32 v89, 0xffff0000, v202
	v_lshlrev_b32_e32 v94, 16, v203
	v_and_b32_e32 v95, 0xffff0000, v203
	v_pk_add_f32 v[86:87], v[86:87], v[94:95]
	v_pk_add_f32 v[84:85], v[84:85], v[88:89]
	v_mul_f32_e32 v89, v87, v87
	v_mul_f32_e32 v88, v85, v85
	v_fmac_f32_e32 v88, v84, v84
	v_fmac_f32_e32 v89, v86, v86
	v_add_f32_e32 v88, v88, v89
	v_add_f32_e32 v93, v93, v88
	v_lshlrev_b32_e32 v88, 16, v200
	v_and_b32_e32 v89, 0xffff0000, v200
	v_lshlrev_b32_e32 v94, 16, v201
	v_and_b32_e32 v95, 0xffff0000, v201
	v_pk_add_f32 v[82:83], v[82:83], v[94:95]
	v_pk_add_f32 v[88:89], v[80:81], v[88:89]
	v_mul_f32_e32 v81, v83, v83
	v_mul_f32_e32 v80, v89, v89
	v_fmac_f32_e32 v80, v88, v88
	v_fmac_f32_e32 v81, v82, v82
	v_add_f32_e32 v80, v80, v81
	v_add_f32_e32 v80, v93, v80
	v_mov_b32_e32 v81, v80
	s_nop 1
	v_permlane16_swap_b32_e32 v80, v81
	v_cvt_pk_bf16_f32 v94, v84, v85
	v_cvt_pk_bf16_f32 v95, v86, v87
	v_cvt_pk_bf16_f32 v103, v90, v91
	s_waitcnt lgkmcnt(0)
	v_add_f32_e32 v80, v80, v81
	v_mov_b32_e32 v81, v80
	s_nop 1
	v_permlane32_swap_b32_e32 v80, v81
	v_cvt_pk_bf16_f32 v96, v88, v89
	v_cvt_pk_bf16_f32 v97, v82, v83
	v_lshl_add_u64 v[98:99], v[98:99], 0, v[250:251]
	s_nop 1
	v_permlane16_swap_b32_e32 v100, v102
	v_permlane16_swap_b32_e32 v101, v103
	global_store_dwordx4 v[98:99], v[100:103], off
	s_nop 1
	s_nop 1
	v_permlane16_swap_b32_e32 v94, v96
	v_permlane16_swap_b32_e32 v95, v97
	global_store_dwordx4 v[98:99], v[94:97], off offset:256
	s_nop 1
	s_and_saveexec_b64 s[38:39], vcc
	s_cbranch_execz .LBB0_1384
	v_lshlrev_b64 v[82:83], 6, v[196:197]
	v_lshl_add_u64 v[82:83], s[14:15], 0, v[82:83]
	v_lshl_add_u64 v[82:83], s[36:37], 2, v[82:83]
	s_lshl_b32 s10, s53, 2
	v_lshl_add_u64 v[82:83], v[82:83], 0, s[10:11]
	s_waitcnt lgkmcnt(0)
	v_add_f32_e32 v80, v80, v81
	global_store_dword v[82:83], v80, off
; #define PG8_GAS __attribute__((address_space(1)))
; __device__ __forceinline__ unsigned pk2_(float lo, float hi) { f32x2c_t v = {lo, hi}; bf16x2c_t b = __builtin_convertvector(v, bf16x2c_t); return __builtin_bit_cast(unsigned, b); }
;     __device__ __forceinline__ void operator()(const f32x4 (&acc)[2][2][4][2], const Unit& u, int wr, int wc, int fr, int fq) const {
;     ...
;         for (int ai = 0; ai < 2; ++ai)
; #pragma unroll
;             for (int m = 0; m < 4; ++m) {
;                 const int r = row0 + ai * HALF + m * 16; const size_t off = (size_t)r * 1024 + col0; float ss = 0.f;
; #pragma unroll
;                 for (int bj = 0; bj < 2; ++bj)
; #pragma unroll
;                     for (int n = 0; n < 2; ++n) {
;                         const u32x2v w0 = bsv[ai][m][bj][n]; f32x4 bs;
;                         bs[0] = __builtin_bit_cast(float, w0.x << 16); bs[1] = __builtin_bit_cast(float, w0.x & 0xffff0000u); bs[2] = __builtin_bit_cast(float, w0.y << 16); bs[3] = __builtin_bit_cast(float, w0.y & 0xffff0000u);
;                         const f32x4 v = bs + acc[ai][bj][m][n] * alpha;
;                         { u32x2v w; w.x = pk2_(v[0], v[1]); w.y = pk2_(v[2], v[3]); *(PG8_GAS u32x2v*)(hb + off + bj * HALF + n * 16) = w; }
;                         ss += (v[0] * v[0] + v[1] * v[1]) + (v[2] * v[2] + v[3] * v[3]);
;                     }
;                 ss += __shfl_xor(ss, 16); ss += __shfl_xor(ss, 32);
;                 if (fq == 0) ((PG8_GAS float*)parts)[(size_t)r * 16 + u.pn * 4 + wc] = ss;
;             }
.LBB0_1384:
	s_or_b64 exec, exec, s[38:39]
	s_waitcnt vmcnt(24)
	v_lshlrev_b32_e32 v80, 16, v198
	s_waitcnt lgkmcnt(0)
	v_and_b32_e32 v81, 0xffff0000, v198
	v_lshlrev_b32_e32 v82, 16, v199
	v_and_b32_e32 v83, 0xffff0000, v199
	v_pk_add_f32 v[76:77], v[76:77], v[80:81]
	v_pk_add_f32 v[78:79], v[78:79], v[82:83]
	v_cvt_pk_bf16_f32 v84, v76, v77
	v_mul_f32_e32 v77, v77, v77
	v_lshl_add_u64 v[82:83], s[12:13], 0, v[194:195]
	v_fmac_f32_e32 v77, v76, v76
	v_mul_f32_e32 v76, v79, v79
	v_cvt_pk_bf16_f32 v85, v78, v79
	v_lshl_add_u64 v[82:83], v[138:139], 1, v[82:83]
	v_fmac_f32_e32 v76, v78, v78
	v_add_f32_e32 v80, v77, v76
	v_lshlrev_b32_e32 v76, 16, v192
	v_and_b32_e32 v77, 0xffff0000, v192
	v_lshlrev_b32_e32 v78, 16, v193
	v_and_b32_e32 v79, 0xffff0000, v193
	v_pk_add_f32 v[72:73], v[72:73], v[76:77]
	v_pk_add_f32 v[74:75], v[74:75], v[78:79]
	v_cvt_pk_bf16_f32 v86, v72, v73
	v_mul_f32_e32 v73, v73, v73
	v_fmac_f32_e32 v73, v72, v72
	v_mul_f32_e32 v72, v75, v75
	v_fmac_f32_e32 v72, v74, v74
	v_add_f32_e32 v72, v73, v72
	v_add_f32_e32 v77, v80, v72
	v_lshlrev_b32_e32 v72, 16, v190
	v_and_b32_e32 v73, 0xffff0000, v190
	v_lshlrev_b32_e32 v78, 16, v191
	v_and_b32_e32 v79, 0xffff0000, v191
	v_pk_add_f32 v[70:71], v[70:71], v[78:79]
	v_pk_add_f32 v[68:69], v[68:69], v[72:73]
	v_mul_f32_e32 v73, v71, v71
	v_mul_f32_e32 v72, v69, v69
	v_fmac_f32_e32 v72, v68, v68
	v_fmac_f32_e32 v73, v70, v70
	v_add_f32_e32 v72, v72, v73
	v_add_f32_e32 v77, v77, v72
	v_lshlrev_b32_e32 v72, 16, v188
	v_and_b32_e32 v73, 0xffff0000, v188
	v_lshlrev_b32_e32 v78, 16, v189
	v_and_b32_e32 v79, 0xffff0000, v189
	v_pk_add_f32 v[66:67], v[66:67], v[78:79]
	v_pk_add_f32 v[72:73], v[64:65], v[72:73]
	v_mul_f32_e32 v65, v67, v67
	v_mul_f32_e32 v64, v73, v73
	v_fmac_f32_e32 v64, v72, v72
	v_fmac_f32_e32 v65, v66, v66
	v_add_f32_e32 v64, v64, v65
	v_add_f32_e32 v64, v77, v64
	v_mov_b32_e32 v65, v64
	s_nop 1
	v_permlane16_swap_b32_e32 v64, v65
	v_cvt_pk_bf16_f32 v78, v68, v69
	v_cvt_pk_bf16_f32 v79, v70, v71
	v_cvt_pk_bf16_f32 v87, v74, v75
	s_waitcnt lgkmcnt(0)
	v_add_f32_e32 v64, v64, v65
	v_mov_b32_e32 v65, v64
	s_nop 1
	v_permlane32_swap_b32_e32 v64, v65
	v_cvt_pk_bf16_f32 v80, v72, v73
	v_cvt_pk_bf16_f32 v81, v66, v67
	v_lshl_add_u64 v[82:83], v[82:83], 0, v[250:251]
	s_nop 1
	v_permlane16_swap_b32_e32 v84, v86
	v_permlane16_swap_b32_e32 v85, v87
	global_store_dwordx4 v[82:83], v[84:87], off
	s_nop 1
	s_nop 1
	v_permlane16_swap_b32_e32 v78, v80
	v_permlane16_swap_b32_e32 v79, v81
	global_store_dwordx4 v[82:83], v[78:81], off offset:256
	s_nop 1
	s_and_saveexec_b64 s[38:39], vcc
	s_cbranch_execz .LBB0_1386
	v_lshlrev_b64 v[66:67], 6, v[184:185]
	v_lshl_add_u64 v[66:67], s[14:15], 0, v[66:67]
	v_lshl_add_u64 v[66:67], s[36:37], 2, v[66:67]
	s_lshl_b32 s10, s53, 2
	v_lshl_add_u64 v[66:67], v[66:67], 0, s[10:11]
	s_waitcnt lgkmcnt(0)
	v_add_f32_e32 v64, v64, v65
	global_store_dword v[66:67], v64, off
.LBB0_1386:
	s_or_b64 exec, exec, s[38:39]
	s_waitcnt vmcnt(22)
	v_lshlrev_b32_e32 v64, 16, v186
	s_waitcnt lgkmcnt(0)
	v_and_b32_e32 v65, 0xffff0000, v186
	v_lshlrev_b32_e32 v66, 16, v187
	v_and_b32_e32 v67, 0xffff0000, v187
	v_pk_add_f32 v[60:61], v[60:61], v[64:65]
	v_pk_add_f32 v[62:63], v[62:63], v[66:67]
	v_cvt_pk_bf16_f32 v68, v60, v61
	v_mul_f32_e32 v61, v61, v61
	v_lshl_add_u64 v[66:67], s[12:13], 0, v[182:183]
	v_fmac_f32_e32 v61, v60, v60
	v_mul_f32_e32 v60, v63, v63
	v_cvt_pk_bf16_f32 v69, v62, v63
	v_lshl_add_u64 v[66:67], v[138:139], 1, v[66:67]
	v_fmac_f32_e32 v60, v62, v62
	v_add_f32_e32 v64, v61, v60
	v_lshlrev_b32_e32 v60, 16, v180
	v_and_b32_e32 v61, 0xffff0000, v180
	v_lshlrev_b32_e32 v62, 16, v181
	v_and_b32_e32 v63, 0xffff0000, v181
	v_pk_add_f32 v[56:57], v[56:57], v[60:61]
	v_pk_add_f32 v[58:59], v[58:59], v[62:63]
	v_cvt_pk_bf16_f32 v70, v56, v57
	v_mul_f32_e32 v57, v57, v57
	v_fmac_f32_e32 v57, v56, v56
	v_mul_f32_e32 v56, v59, v59
	v_fmac_f32_e32 v56, v58, v58
	v_add_f32_e32 v56, v57, v56
	v_add_f32_e32 v61, v64, v56
	v_lshlrev_b32_e32 v56, 16, v178
	v_and_b32_e32 v57, 0xffff0000, v178
	v_lshlrev_b32_e32 v62, 16, v179
	v_and_b32_e32 v63, 0xffff0000, v179
	v_pk_add_f32 v[54:55], v[54:55], v[62:63]
	v_pk_add_f32 v[52:53], v[52:53], v[56:57]
	v_mul_f32_e32 v57, v55, v55
	v_mul_f32_e32 v56, v53, v53
	v_fmac_f32_e32 v56, v52, v52
	v_fmac_f32_e32 v57, v54, v54
	v_add_f32_e32 v56, v56, v57
	v_add_f32_e32 v61, v61, v56
	v_lshlrev_b32_e32 v56, 16, v176
	v_and_b32_e32 v57, 0xffff0000, v176
	v_lshlrev_b32_e32 v62, 16, v177
	v_and_b32_e32 v63, 0xffff0000, v177
	v_pk_add_f32 v[50:51], v[50:51], v[62:63]
	v_pk_add_f32 v[56:57], v[48:49], v[56:57]
	v_mul_f32_e32 v49, v51, v51
	v_mul_f32_e32 v48, v57, v57
	v_fmac_f32_e32 v48, v56, v56
	v_fmac_f32_e32 v49, v50, v50
	v_add_f32_e32 v48, v48, v49
	v_add_f32_e32 v48, v61, v48
	v_mov_b32_e32 v49, v48
	s_nop 1
	v_permlane16_swap_b32_e32 v48, v49
	v_cvt_pk_bf16_f32 v62, v52, v53
	v_cvt_pk_bf16_f32 v63, v54, v55
	v_cvt_pk_bf16_f32 v71, v58, v59
	s_waitcnt lgkmcnt(0)
	v_add_f32_e32 v48, v48, v49
	v_mov_b32_e32 v49, v48
	s_nop 1
	v_permlane32_swap_b32_e32 v48, v49
	v_cvt_pk_bf16_f32 v64, v56, v57
	v_cvt_pk_bf16_f32 v65, v50, v51
	v_lshl_add_u64 v[66:67], v[66:67], 0, v[250:251]
	s_nop 1
	v_permlane16_swap_b32_e32 v68, v70
	v_permlane16_swap_b32_e32 v69, v71
	global_store_dwordx4 v[66:67], v[68:71], off
	s_nop 1
	s_nop 1
	v_permlane16_swap_b32_e32 v62, v64
	v_permlane16_swap_b32_e32 v63, v65
	global_store_dwordx4 v[66:67], v[62:65], off offset:256
	s_nop 1
	s_and_saveexec_b64 s[38:39], vcc
	s_cbranch_execz .LBB0_1388
	v_lshlrev_b64 v[50:51], 6, v[172:173]
	v_lshl_add_u64 v[50:51], s[14:15], 0, v[50:51]
	v_lshl_add_u64 v[50:51], s[36:37], 2, v[50:51]
	s_lshl_b32 s10, s53, 2
	v_lshl_add_u64 v[50:51], v[50:51], 0, s[10:11]
	s_waitcnt lgkmcnt(0)
	v_add_f32_e32 v48, v48, v49
	global_store_dword v[50:51], v48, off
; #define PG8_GAS __attribute__((address_space(1)))
; __device__ __forceinline__ unsigned pk2_(float lo, float hi) { f32x2c_t v = {lo, hi}; bf16x2c_t b = __builtin_convertvector(v, bf16x2c_t); return __builtin_bit_cast(unsigned, b); }
;     __device__ __forceinline__ void operator()(const f32x4 (&acc)[2][2][4][2], const Unit& u, int wr, int wc, int fr, int fq) const {
;     ...
;         for (int ai = 0; ai < 2; ++ai)
; #pragma unroll
;             for (int m = 0; m < 4; ++m) {
;                 const int r = row0 + ai * HALF + m * 16; const size_t off = (size_t)r * 1024 + col0; float ss = 0.f;
; #pragma unroll
;                 for (int bj = 0; bj < 2; ++bj)
; #pragma unroll
;                     for (int n = 0; n < 2; ++n) {
;                         const u32x2v w0 = bsv[ai][m][bj][n]; f32x4 bs;
;                         bs[0] = __builtin_bit_cast(float, w0.x << 16); bs[1] = __builtin_bit_cast(float, w0.x & 0xffff0000u); bs[2] = __builtin_bit_cast(float, w0.y << 16); bs[3] = __builtin_bit_cast(float, w0.y & 0xffff0000u);
;                         const f32x4 v = bs + acc[ai][bj][m][n] * alpha;
;                         { u32x2v w; w.x = pk2_(v[0], v[1]); w.y = pk2_(v[2], v[3]); *(PG8_GAS u32x2v*)(hb + off + bj * HALF + n * 16) = w; }
;                         ss += (v[0] * v[0] + v[1] * v[1]) + (v[2] * v[2] + v[3] * v[3]);
;                     }
;                 ss += __shfl_xor(ss, 16); ss += __shfl_xor(ss, 32);
;                 if (fq == 0) ((PG8_GAS float*)parts)[(size_t)r * 16 + u.pn * 4 + wc] = ss;
;             }
.LBB0_1388:
	s_or_b64 exec, exec, s[38:39]
	s_waitcnt vmcnt(20)
	v_lshlrev_b32_e32 v48, 16, v174
	s_waitcnt lgkmcnt(0)
	v_and_b32_e32 v49, 0xffff0000, v174
	v_lshlrev_b32_e32 v50, 16, v175
	v_and_b32_e32 v51, 0xffff0000, v175
	v_pk_add_f32 v[44:45], v[44:45], v[48:49]
	v_pk_add_f32 v[46:47], v[46:47], v[50:51]
	v_cvt_pk_bf16_f32 v52, v44, v45
	v_mul_f32_e32 v45, v45, v45
	v_lshl_add_u64 v[50:51], s[12:13], 0, v[170:171]
	v_fmac_f32_e32 v45, v44, v44
	v_mul_f32_e32 v44, v47, v47
	v_cvt_pk_bf16_f32 v53, v46, v47
	v_lshl_add_u64 v[50:51], v[138:139], 1, v[50:51]
	v_fmac_f32_e32 v44, v46, v46
	v_add_f32_e32 v48, v45, v44
	v_lshlrev_b32_e32 v44, 16, v168
	v_and_b32_e32 v45, 0xffff0000, v168
	v_lshlrev_b32_e32 v46, 16, v169
	v_and_b32_e32 v47, 0xffff0000, v169
	v_pk_add_f32 v[40:41], v[40:41], v[44:45]
	v_pk_add_f32 v[42:43], v[42:43], v[46:47]
	v_cvt_pk_bf16_f32 v54, v40, v41
	v_mul_f32_e32 v41, v41, v41
	v_fmac_f32_e32 v41, v40, v40
	v_mul_f32_e32 v40, v43, v43
	v_fmac_f32_e32 v40, v42, v42
	v_add_f32_e32 v40, v41, v40
	v_add_f32_e32 v45, v48, v40
	v_lshlrev_b32_e32 v40, 16, v166
	v_and_b32_e32 v41, 0xffff0000, v166
	v_lshlrev_b32_e32 v46, 16, v167
	v_and_b32_e32 v47, 0xffff0000, v167
	v_pk_add_f32 v[38:39], v[38:39], v[46:47]
	v_pk_add_f32 v[36:37], v[36:37], v[40:41]
	v_mul_f32_e32 v41, v39, v39
	v_mul_f32_e32 v40, v37, v37
	v_fmac_f32_e32 v40, v36, v36
	v_fmac_f32_e32 v41, v38, v38
	v_add_f32_e32 v40, v40, v41
	v_add_f32_e32 v45, v45, v40
	v_lshlrev_b32_e32 v40, 16, v164
	v_and_b32_e32 v41, 0xffff0000, v164
	v_lshlrev_b32_e32 v46, 16, v165
	v_and_b32_e32 v47, 0xffff0000, v165
	v_pk_add_f32 v[34:35], v[34:35], v[46:47]
	v_pk_add_f32 v[40:41], v[32:33], v[40:41]
	v_mul_f32_e32 v33, v35, v35
	v_mul_f32_e32 v32, v41, v41
	v_fmac_f32_e32 v32, v40, v40
	v_fmac_f32_e32 v33, v34, v34
	v_add_f32_e32 v32, v32, v33
	v_add_f32_e32 v32, v45, v32
	v_mov_b32_e32 v33, v32
	s_nop 1
	v_permlane16_swap_b32_e32 v32, v33
	v_cvt_pk_bf16_f32 v46, v36, v37
	v_cvt_pk_bf16_f32 v47, v38, v39
	v_cvt_pk_bf16_f32 v55, v42, v43
	s_waitcnt lgkmcnt(0)
	v_add_f32_e32 v32, v32, v33
	v_mov_b32_e32 v33, v32
	s_nop 1
	v_permlane32_swap_b32_e32 v32, v33
	v_cvt_pk_bf16_f32 v48, v40, v41
	v_cvt_pk_bf16_f32 v49, v34, v35
	v_lshl_add_u64 v[50:51], v[50:51], 0, v[250:251]
	s_nop 1
	v_permlane16_swap_b32_e32 v52, v54
	v_permlane16_swap_b32_e32 v53, v55
	global_store_dwordx4 v[50:51], v[52:55], off
	s_nop 1
	s_nop 1
	v_permlane16_swap_b32_e32 v46, v48
	v_permlane16_swap_b32_e32 v47, v49
	global_store_dwordx4 v[50:51], v[46:49], off offset:256
	s_nop 1
	s_and_saveexec_b64 s[38:39], vcc
	s_cbranch_execz .LBB0_1390
	v_lshlrev_b64 v[34:35], 6, v[160:161]
	v_lshl_add_u64 v[34:35], s[14:15], 0, v[34:35]
	v_lshl_add_u64 v[34:35], s[36:37], 2, v[34:35]
	s_lshl_b32 s10, s53, 2
	v_lshl_add_u64 v[34:35], v[34:35], 0, s[10:11]
	s_waitcnt lgkmcnt(0)
	v_add_f32_e32 v32, v32, v33
	global_store_dword v[34:35], v32, off
; #define PG8_GAS __attribute__((address_space(1)))
; __device__ __forceinline__ unsigned pk2_(float lo, float hi) { f32x2c_t v = {lo, hi}; bf16x2c_t b = __builtin_convertvector(v, bf16x2c_t); return __builtin_bit_cast(unsigned, b); }
;     __device__ __forceinline__ void operator()(const f32x4 (&acc)[2][2][4][2], const Unit& u, int wr, int wc, int fr, int fq) const {
;     ...
;         for (int ai = 0; ai < 2; ++ai)
; #pragma unroll
;             for (int m = 0; m < 4; ++m) {
;                 const int r = row0 + ai * HALF + m * 16; const size_t off = (size_t)r * 1024 + col0; float ss = 0.f;
; #pragma unroll
;                 for (int bj = 0; bj < 2; ++bj)
; #pragma unroll
;                     for (int n = 0; n < 2; ++n) {
;                         const u32x2v w0 = bsv[ai][m][bj][n]; f32x4 bs;
;                         bs[0] = __builtin_bit_cast(float, w0.x << 16); bs[1] = __builtin_bit_cast(float, w0.x & 0xffff0000u); bs[2] = __builtin_bit_cast(float, w0.y << 16); bs[3] = __builtin_bit_cast(float, w0.y & 0xffff0000u);
;                         const f32x4 v = bs + acc[ai][bj][m][n] * alpha;
;                         { u32x2v w; w.x = pk2_(v[0], v[1]); w.y = pk2_(v[2], v[3]); *(PG8_GAS u32x2v*)(hb + off + bj * HALF + n * 16) = w; }
;                         ss += (v[0] * v[0] + v[1] * v[1]) + (v[2] * v[2] + v[3] * v[3]);
;                     }
;                 ss += __shfl_xor(ss, 16); ss += __shfl_xor(ss, 32);
;                 if (fq == 0) ((PG8_GAS float*)parts)[(size_t)r * 16 + u.pn * 4 + wc] = ss;
;             }
.LBB0_1390:
	s_or_b64 exec, exec, s[38:39]
	s_waitcnt vmcnt(18)
	v_lshlrev_b32_e32 v32, 16, v162
	s_waitcnt lgkmcnt(0)
	v_and_b32_e32 v33, 0xffff0000, v162
	v_lshlrev_b32_e32 v34, 16, v163
	v_and_b32_e32 v35, 0xffff0000, v163
	v_pk_add_f32 v[28:29], v[28:29], v[32:33]
	v_pk_add_f32 v[30:31], v[30:31], v[34:35]
	v_cvt_pk_bf16_f32 v36, v28, v29
	v_mul_f32_e32 v29, v29, v29
	v_lshl_add_u64 v[34:35], s[12:13], 0, v[158:159]
	v_fmac_f32_e32 v29, v28, v28
	v_mul_f32_e32 v28, v31, v31
	v_cvt_pk_bf16_f32 v37, v30, v31
	v_lshl_add_u64 v[34:35], v[138:139], 1, v[34:35]
	v_fmac_f32_e32 v28, v30, v30
	v_add_f32_e32 v32, v29, v28
	v_lshlrev_b32_e32 v28, 16, v156
	v_and_b32_e32 v29, 0xffff0000, v156
	v_lshlrev_b32_e32 v30, 16, v157
	v_and_b32_e32 v31, 0xffff0000, v157
	v_pk_add_f32 v[24:25], v[24:25], v[28:29]
	v_pk_add_f32 v[26:27], v[26:27], v[30:31]
	v_cvt_pk_bf16_f32 v38, v24, v25
	v_mul_f32_e32 v25, v25, v25
	v_fmac_f32_e32 v25, v24, v24
	v_mul_f32_e32 v24, v27, v27
	v_fmac_f32_e32 v24, v26, v26
	v_add_f32_e32 v24, v25, v24
	v_add_f32_e32 v29, v32, v24
	v_lshlrev_b32_e32 v24, 16, v154
	v_and_b32_e32 v25, 0xffff0000, v154
	v_lshlrev_b32_e32 v30, 16, v155
	v_and_b32_e32 v31, 0xffff0000, v155
	v_pk_add_f32 v[22:23], v[22:23], v[30:31]
	v_pk_add_f32 v[20:21], v[20:21], v[24:25]
	v_mul_f32_e32 v25, v23, v23
	v_mul_f32_e32 v24, v21, v21
	v_fmac_f32_e32 v24, v20, v20
	v_fmac_f32_e32 v25, v22, v22
	v_add_f32_e32 v24, v24, v25
	v_add_f32_e32 v29, v29, v24
	v_lshlrev_b32_e32 v24, 16, v152
	v_and_b32_e32 v25, 0xffff0000, v152
	v_lshlrev_b32_e32 v30, 16, v153
	v_and_b32_e32 v31, 0xffff0000, v153
	v_pk_add_f32 v[18:19], v[18:19], v[30:31]
	v_pk_add_f32 v[24:25], v[16:17], v[24:25]
	v_mul_f32_e32 v17, v19, v19
	v_mul_f32_e32 v16, v25, v25
	v_fmac_f32_e32 v16, v24, v24
	v_fmac_f32_e32 v17, v18, v18
	v_add_f32_e32 v16, v16, v17
	v_add_f32_e32 v16, v29, v16
	v_mov_b32_e32 v17, v16
	s_nop 1
	v_permlane16_swap_b32_e32 v16, v17
	v_cvt_pk_bf16_f32 v30, v20, v21
	v_cvt_pk_bf16_f32 v31, v22, v23
	v_cvt_pk_bf16_f32 v39, v26, v27
	s_waitcnt lgkmcnt(0)
	v_add_f32_e32 v16, v16, v17
	v_mov_b32_e32 v17, v16
	s_nop 1
	v_permlane32_swap_b32_e32 v16, v17
	v_cvt_pk_bf16_f32 v32, v24, v25
	v_cvt_pk_bf16_f32 v33, v18, v19
	v_lshl_add_u64 v[34:35], v[34:35], 0, v[250:251]
	s_nop 1
	v_permlane16_swap_b32_e32 v36, v38
	v_permlane16_swap_b32_e32 v37, v39
	global_store_dwordx4 v[34:35], v[36:39], off
	s_nop 1
	s_nop 1
	v_permlane16_swap_b32_e32 v30, v32
	v_permlane16_swap_b32_e32 v31, v33
	global_store_dwordx4 v[34:35], v[30:33], off offset:256
	s_nop 1
	s_and_saveexec_b64 s[38:39], vcc
	s_cbranch_execz .LBB0_1392
	v_lshlrev_b64 v[18:19], 6, v[148:149]
	v_lshl_add_u64 v[18:19], s[14:15], 0, v[18:19]
	v_lshl_add_u64 v[18:19], s[36:37], 2, v[18:19]
	s_lshl_b32 s10, s53, 2
	v_lshl_add_u64 v[18:19], v[18:19], 0, s[10:11]
	s_waitcnt lgkmcnt(0)
	v_add_f32_e32 v16, v16, v17
	global_store_dword v[18:19], v16, off
.LBB0_1392:
	s_or_b64 exec, exec, s[38:39]
	s_waitcnt vmcnt(16)
	v_lshlrev_b32_e32 v16, 16, v150
	s_waitcnt lgkmcnt(0)
	v_and_b32_e32 v17, 0xffff0000, v150
	v_lshlrev_b32_e32 v18, 16, v151
	v_and_b32_e32 v19, 0xffff0000, v151
	v_pk_add_f32 v[12:13], v[12:13], v[16:17]
	v_pk_add_f32 v[14:15], v[14:15], v[18:19]
	v_cvt_pk_bf16_f32 v20, v12, v13
	v_mul_f32_e32 v13, v13, v13
	v_lshl_add_u64 v[18:19], s[12:13], 0, v[146:147]
	v_fmac_f32_e32 v13, v12, v12
	v_mul_f32_e32 v12, v15, v15
	v_cvt_pk_bf16_f32 v21, v14, v15
	v_lshl_add_u64 v[18:19], v[138:139], 1, v[18:19]
	v_fmac_f32_e32 v12, v14, v14
	v_add_f32_e32 v16, v13, v12
	v_lshlrev_b32_e32 v12, 16, v144
	v_and_b32_e32 v13, 0xffff0000, v144
	v_lshlrev_b32_e32 v14, 16, v145
	v_and_b32_e32 v15, 0xffff0000, v145
	v_pk_add_f32 v[8:9], v[8:9], v[12:13]
	v_pk_add_f32 v[10:11], v[10:11], v[14:15]
	v_cvt_pk_bf16_f32 v22, v8, v9
	v_mul_f32_e32 v9, v9, v9
	v_fmac_f32_e32 v9, v8, v8
	v_mul_f32_e32 v8, v11, v11
	v_fmac_f32_e32 v8, v10, v10
	v_add_f32_e32 v8, v9, v8
	v_add_f32_e32 v13, v16, v8
	v_lshlrev_b32_e32 v8, 16, v142
	v_and_b32_e32 v9, 0xffff0000, v142
	v_lshlrev_b32_e32 v14, 16, v143
	v_and_b32_e32 v15, 0xffff0000, v143
	v_pk_add_f32 v[6:7], v[6:7], v[14:15]
	v_pk_add_f32 v[4:5], v[4:5], v[8:9]
	v_mul_f32_e32 v9, v7, v7
	v_mul_f32_e32 v8, v5, v5
	v_fmac_f32_e32 v8, v4, v4
	v_fmac_f32_e32 v9, v6, v6
	v_add_f32_e32 v8, v8, v9
	v_add_f32_e32 v13, v13, v8
	v_lshlrev_b32_e32 v8, 16, v140
	v_and_b32_e32 v9, 0xffff0000, v140
	v_lshlrev_b32_e32 v14, 16, v141
	v_and_b32_e32 v15, 0xffff0000, v141
	v_pk_add_f32 v[2:3], v[2:3], v[14:15]
	v_pk_add_f32 v[8:9], v[0:1], v[8:9]
	v_mul_f32_e32 v1, v3, v3
	v_mul_f32_e32 v0, v9, v9
	v_fmac_f32_e32 v0, v8, v8
	v_fmac_f32_e32 v1, v2, v2
	v_add_f32_e32 v0, v0, v1
	v_add_f32_e32 v0, v13, v0
	v_mov_b32_e32 v1, v0
	s_nop 1
	v_permlane16_swap_b32_e32 v0, v1
	v_cvt_pk_bf16_f32 v14, v4, v5
	v_cvt_pk_bf16_f32 v15, v6, v7
	v_cvt_pk_bf16_f32 v23, v10, v11
	s_waitcnt lgkmcnt(0)
	v_add_f32_e32 v0, v0, v1
	v_mov_b32_e32 v1, v0
	s_nop 1
	v_permlane32_swap_b32_e32 v0, v1
	v_cvt_pk_bf16_f32 v16, v8, v9
	v_cvt_pk_bf16_f32 v17, v2, v3
	v_lshl_add_u64 v[18:19], v[18:19], 0, v[250:251]
	s_nop 1
	v_permlane16_swap_b32_e32 v20, v22
	v_permlane16_swap_b32_e32 v21, v23
	global_store_dwordx4 v[18:19], v[20:23], off
	s_nop 1
	s_nop 1
	v_permlane16_swap_b32_e32 v14, v16
	v_permlane16_swap_b32_e32 v15, v17
	global_store_dwordx4 v[18:19], v[14:17], off offset:256
	s_nop 1
	s_and_saveexec_b64 s[38:39], vcc
	s_cbranch_execz .LBB0_1394
	v_lshlrev_b64 v[2:3], 6, v[136:137]
	v_lshl_add_u64 v[2:3], s[14:15], 0, v[2:3]
	v_lshl_add_u64 v[2:3], s[36:37], 2, v[2:3]
	s_lshl_b32 s10, s53, 2
	v_lshl_add_u64 v[2:3], v[2:3], 0, s[10:11]
	s_waitcnt lgkmcnt(0)
	v_add_f32_e32 v0, v0, v1
	global_store_dword v[2:3], v0, off

; #define PG8_GAS __attribute__((address_space(1)))
; __device__ __forceinline__ unsigned pk2_(float lo, float hi) { f32x2c_t v = {lo, hi}; bf16x2c_t b = __builtin_convertvector(v, bf16x2c_t); return __builtin_bit_cast(unsigned, b); }
;     __device__ __forceinline__ void operator()(const f32x4 (&acc)[2][2][4][2], const Unit& u, int wr, int wc, int fr, int fq) const {
;         typedef unsigned u32x2v __attribute__((ext_vector_type(2)));
;         const int row0 = u.pm * BM + wr * 64 + fr, col0 = u.pn * BM + wc * 32 + 4 * fq;
;         u32x2v bsv[2][4][2][2];
; #pragma unroll
;         for (int ai = 0; ai < 2; ++ai)
; #pragma unroll
;             for (int m = 0; m < 4; ++m) { const size_t off = (size_t)(row0 + ai * HALF + m * 16) * 1024 + col0;
; #pragma unroll
;                 for (int bj = 0; bj < 2; ++bj)
; #pragma unroll
;                     for (int n = 0; n < 2; ++n) bsv[ai][m][bj][n] = *(const PG8_GAS u32x2v*)(hbase + off + bj * HALF + n * 16); }
; #pragma unroll
;         for (int ai = 0; ai < 2; ++ai)
; #pragma unroll
;             for (int m = 0; m < 4; ++m) {
;                 const int r = row0 + ai * HALF + m * 16; const size_t off = (size_t)r * 1024 + col0; float ss = 0.f;
; #pragma unroll
;                 for (int bj = 0; bj < 2; ++bj)
; #pragma unroll
;                     for (int n = 0; n < 2; ++n) {
;                         const u32x2v w0 = bsv[ai][m][bj][n]; f32x4 bs;
;                         bs[0] = __builtin_bit_cast(float, w0.x << 16); bs[1] = __builtin_bit_cast(float, w0.x & 0xffff0000u); bs[2] = __builtin_bit_cast(float, w0.y << 16); bs[3] = __builtin_bit_cast(float, w0.y & 0xffff0000u);
;                         const f32x4 v = bs + acc[ai][bj][m][n] * alpha;
;                         { u32x2v w; w.x = pk2_(v[0], v[1]); w.y = pk2_(v[2], v[3]); *(PG8_GAS u32x2v*)(hb + off + bj * HALF + n * 16) = w; }
;                         ss += (v[0] * v[0] + v[1] * v[1]) + (v[2] * v[2] + v[3] * v[3]);
;                     }
;                 ss += __shfl_xor(ss, 16); ss += __shfl_xor(ss, 32);
;                 if (fq == 0) ((PG8_GAS float*)parts)[(size_t)r * 16 + u.pn * 4 + wc] = ss;
;             }
;     }
.LBB0_1735:
	s_lshl_b32 s30, s57, 8
	v_mov_b32_e32 v136, v252
	s_add_i32 s30, s30, s48
	v_cmp_lt_i32_e32 vcc, v227, v226
	v_and_or_b32 v220, v136, 15, s30
	s_lshl_b32 s30, s12, 8
	v_bfe_u32 v244, v136, 4, 2
	s_or_b32 s30, s30, s49
	v_lshl_or_b32 v138, v244, 2, s30
	v_ashrrev_i32_e32 v139, 31, v138
	v_lshlrev_b64 v[224:225], 1, v[138:139]
	v_ashrrev_i32_e32 v221, 31, v220
	v_lshl_add_u64 v[140:141], s[14:15], 0, v[224:225]
	v_lshlrev_b64 v[234:235], 11, v[220:221]
	v_lshl_add_u64 v[136:137], v[140:141], 0, v[234:235]
	global_load_dwordx2 v[236:237], v[136:137], off
	global_load_dwordx2 v[238:239], v[136:137], off offset:32
	global_load_dwordx2 v[240:241], v[136:137], off offset:256
	global_load_dwordx2 v[242:243], v[136:137], off offset:288
	v_or_b32_e32 v208, 16, v220
	v_ashrrev_i32_e32 v209, 31, v208
	v_or_b32_e32 v196, 32, v220
	v_lshlrev_b64 v[218:219], 11, v[208:209]
	v_ashrrev_i32_e32 v197, 31, v196
	v_or_b32_e32 v184, 48, v220
	v_lshl_add_u64 v[136:137], v[140:141], 0, v[218:219]
	v_lshlrev_b64 v[206:207], 11, v[196:197]
	v_ashrrev_i32_e32 v185, 31, v184
	v_add_u32_e32 v172, 0x80, v220
	global_load_dwordx2 v[222:223], v[136:137], off
	global_load_dwordx2 v[216:217], v[136:137], off offset:32
	global_load_dwordx2 v[214:215], v[136:137], off offset:256
	global_load_dwordx2 v[212:213], v[136:137], off offset:288
	v_lshl_add_u64 v[136:137], v[140:141], 0, v[206:207]
	v_lshlrev_b64 v[194:195], 11, v[184:185]
	v_ashrrev_i32_e32 v173, 31, v172
	v_add_u32_e32 v160, 0x90, v220
	global_load_dwordx2 v[210:211], v[136:137], off
	global_load_dwordx2 v[204:205], v[136:137], off offset:32
	global_load_dwordx2 v[202:203], v[136:137], off offset:256
	global_load_dwordx2 v[200:201], v[136:137], off offset:288
	v_lshl_add_u64 v[136:137], v[140:141], 0, v[194:195]
	v_lshlrev_b64 v[182:183], 11, v[172:173]
	v_ashrrev_i32_e32 v161, 31, v160
	v_add_u32_e32 v148, 0xa0, v220
	global_load_dwordx2 v[198:199], v[136:137], off
	global_load_dwordx2 v[192:193], v[136:137], off offset:32
	global_load_dwordx2 v[190:191], v[136:137], off offset:256
	global_load_dwordx2 v[188:189], v[136:137], off offset:288
	v_lshl_add_u64 v[136:137], v[140:141], 0, v[182:183]
	v_lshlrev_b64 v[170:171], 11, v[160:161]
	v_ashrrev_i32_e32 v149, 31, v148
	global_load_dwordx2 v[186:187], v[136:137], off
	global_load_dwordx2 v[180:181], v[136:137], off offset:32
	global_load_dwordx2 v[178:179], v[136:137], off offset:256
	global_load_dwordx2 v[176:177], v[136:137], off offset:288
	v_lshl_add_u64 v[136:137], v[140:141], 0, v[170:171]
	v_lshlrev_b64 v[158:159], 11, v[148:149]
	global_load_dwordx2 v[174:175], v[136:137], off
	global_load_dwordx2 v[168:169], v[136:137], off offset:32
	global_load_dwordx2 v[166:167], v[136:137], off offset:256
	global_load_dwordx2 v[164:165], v[136:137], off offset:288
	v_lshl_add_u64 v[136:137], v[140:141], 0, v[158:159]
	global_load_dwordx2 v[162:163], v[136:137], off
	global_load_dwordx2 v[156:157], v[136:137], off offset:32
	global_load_dwordx2 v[154:155], v[136:137], off offset:256
	global_load_dwordx2 v[152:153], v[136:137], off offset:288
	v_add_u32_e32 v136, 0xb0, v220
	v_ashrrev_i32_e32 v137, 31, v136
	v_lshlrev_b64 v[146:147], 11, v[136:137]
	v_lshl_add_u64 v[140:141], v[140:141], 0, v[146:147]
	global_load_dwordx2 v[150:151], v[140:141], off
	global_load_dwordx2 v[144:145], v[140:141], off offset:32
	global_load_dwordx2 v[142:143], v[140:141], off offset:256
	s_nop 0
	global_load_dwordx2 v[140:141], v[140:141], off offset:288
	v_bfe_u32 v250, v252, 4, 1
	v_mul_u32_u24_e32 v250, 24, v250
	v_mov_b32_e32 v251, 0
	v_xor_b32_e32 v245, 32, v253
	v_cndmask_b32_e32 v232, v253, v227, vcc
	v_cmp_lt_i32_e32 vcc, v245, v226
	v_lshlrev_b32_e32 v233, 2, v232
	v_lshl_add_u64 v[234:235], s[14:15], 0, v[234:235]
	v_cndmask_b32_e32 v232, v253, v245, vcc
	v_cmp_eq_u32_e32 vcc, 0, v244
	v_lshl_add_u64 v[224:225], v[234:235], 0, v[224:225]
	v_lshlrev_b32_e32 v232, 2, v232
	s_lshl_b32 s30, s12, 2
	s_ashr_i32 s31, s30, 31
	s_waitcnt vmcnt(28)
	v_lshlrev_b32_e32 v244, 16, v236
	v_and_b32_e32 v245, 0xffff0000, v236
	v_lshlrev_b32_e32 v236, 16, v237
	v_and_b32_e32 v237, 0xffff0000, v237
	v_pk_fma_f32 v[124:125], v[124:125], 0.5, v[244:245] op_sel_hi:[1,0,1]
	v_pk_fma_f32 v[126:127], v[126:127], 0.5, v[236:237] op_sel_hi:[1,0,1]
	v_cvt_pk_bf16_f32 v236, v124, v125
	v_mul_f32_e32 v125, v125, v125
	v_fmac_f32_e32 v125, v124, v124
	v_mul_f32_e32 v124, v127, v127
	v_fmac_f32_e32 v124, v126, v126
	v_add_f32_e32 v234, v125, v124
	v_lshlrev_b32_e32 v124, 16, v238
	v_and_b32_e32 v125, 0xffff0000, v238
	v_cvt_pk_bf16_f32 v237, v126, v127
	v_lshlrev_b32_e32 v126, 16, v239
	v_and_b32_e32 v127, 0xffff0000, v239
	v_pk_fma_f32 v[120:121], v[120:121], 0.5, v[124:125] op_sel_hi:[1,0,1]
	v_pk_fma_f32 v[122:123], v[122:123], 0.5, v[126:127] op_sel_hi:[1,0,1]
	v_cvt_pk_bf16_f32 v124, v120, v121
	v_mul_f32_e32 v121, v121, v121
	v_fmac_f32_e32 v121, v120, v120
	v_mul_f32_e32 v120, v123, v123
	v_fmac_f32_e32 v120, v122, v122
	v_add_f32_e32 v120, v121, v120
	v_add_f32_e32 v125, v234, v120
	v_lshlrev_b32_e32 v120, 16, v240
	v_and_b32_e32 v121, 0xffff0000, v240
	v_lshlrev_b32_e32 v126, 16, v241
	v_and_b32_e32 v127, 0xffff0000, v241
	v_pk_fma_f32 v[118:119], v[118:119], 0.5, v[126:127] op_sel_hi:[1,0,1]
	v_pk_fma_f32 v[116:117], v[116:117], 0.5, v[120:121] op_sel_hi:[1,0,1]
	v_mul_f32_e32 v121, v119, v119
	v_mul_f32_e32 v120, v117, v117
	v_fmac_f32_e32 v120, v116, v116
	v_fmac_f32_e32 v121, v118, v118
	v_add_f32_e32 v120, v120, v121
	v_add_f32_e32 v125, v125, v120
	v_lshlrev_b32_e32 v120, 16, v242
	v_and_b32_e32 v121, 0xffff0000, v242
	v_lshlrev_b32_e32 v126, 16, v243
	v_and_b32_e32 v127, 0xffff0000, v243
	v_pk_fma_f32 v[114:115], v[114:115], 0.5, v[126:127] op_sel_hi:[1,0,1]
	v_pk_fma_f32 v[120:121], v[112:113], 0.5, v[120:121] op_sel_hi:[1,0,1]
	v_mul_f32_e32 v113, v115, v115
	v_mul_f32_e32 v112, v121, v121
	v_fmac_f32_e32 v112, v120, v120
	v_fmac_f32_e32 v113, v114, v114
	v_add_f32_e32 v112, v112, v113
	v_add_f32_e32 v112, v125, v112
	v_mov_b32_e32 v113, v112
	s_nop 1
	v_permlane16_swap_b32_e32 v112, v113
	v_cvt_pk_bf16_f32 v116, v116, v117
	v_cvt_pk_bf16_f32 v117, v118, v119
	v_cvt_pk_bf16_f32 v125, v122, v123
	global_store_dwordx2 v[224:225], v[116:117], off offset:256
	s_waitcnt lgkmcnt(0)
	v_add_f32_e32 v112, v112, v113
	v_mov_b32_e32 v113, v112
	s_nop 1
	v_permlane32_swap_b32_e32 v112, v113
	v_cvt_pk_bf16_f32 v116, v120, v121
	v_cvt_pk_bf16_f32 v117, v114, v115
	global_store_dwordx2 v[224:225], v[236:237], off
	global_store_dwordx2 v[224:225], v[124:125], off offset:32
	global_store_dwordx2 v[224:225], v[116:117], off offset:288
	s_and_saveexec_b64 s[34:35], vcc
	s_cbranch_execz .LBB0_1737
	v_lshlrev_b64 v[114:115], 6, v[220:221]
	v_lshl_add_u64 v[114:115], s[16:17], 0, v[114:115]
	v_lshl_add_u64 v[114:115], s[30:31], 2, v[114:115]
	s_lshl_b32 s12, s47, 2
	v_lshl_add_u64 v[114:115], v[114:115], 0, s[12:13]
	s_waitcnt lgkmcnt(0)
	v_add_f32_e32 v112, v112, v113
	global_store_dword v[114:115], v112, off
; #define PG8_GAS __attribute__((address_space(1)))
; __device__ __forceinline__ unsigned pk2_(float lo, float hi) { f32x2c_t v = {lo, hi}; bf16x2c_t b = __builtin_convertvector(v, bf16x2c_t); return __builtin_bit_cast(unsigned, b); }
;     __device__ __forceinline__ void operator()(const f32x4 (&acc)[2][2][4][2], const Unit& u, int wr, int wc, int fr, int fq) const {
;     ...
;         for (int ai = 0; ai < 2; ++ai)
; #pragma unroll
;             for (int m = 0; m < 4; ++m) {
;                 const int r = row0 + ai * HALF + m * 16; const size_t off = (size_t)r * 1024 + col0; float ss = 0.f;
; #pragma unroll
;                 for (int bj = 0; bj < 2; ++bj)
; #pragma unroll
;                     for (int n = 0; n < 2; ++n) {
;                         const u32x2v w0 = bsv[ai][m][bj][n]; f32x4 bs;
;                         bs[0] = __builtin_bit_cast(float, w0.x << 16); bs[1] = __builtin_bit_cast(float, w0.x & 0xffff0000u); bs[2] = __builtin_bit_cast(float, w0.y << 16); bs[3] = __builtin_bit_cast(float, w0.y & 0xffff0000u);
;                         const f32x4 v = bs + acc[ai][bj][m][n] * alpha;
;                         { u32x2v w; w.x = pk2_(v[0], v[1]); w.y = pk2_(v[2], v[3]); *(PG8_GAS u32x2v*)(hb + off + bj * HALF + n * 16) = w; }
;                         ss += (v[0] * v[0] + v[1] * v[1]) + (v[2] * v[2] + v[3] * v[3]);
;                     }
;                 ss += __shfl_xor(ss, 16); ss += __shfl_xor(ss, 32);
;                 if (fq == 0) ((PG8_GAS float*)parts)[(size_t)r * 16 + u.pn * 4 + wc] = ss;
;             }
.LBB0_1737:
	s_or_b64 exec, exec, s[34:35]
	s_waitcnt vmcnt(28)
	v_lshlrev_b32_e32 v112, 16, v222
	s_waitcnt lgkmcnt(0)
	v_and_b32_e32 v113, 0xffff0000, v222
	v_lshlrev_b32_e32 v114, 16, v223
	v_and_b32_e32 v115, 0xffff0000, v223
	v_pk_fma_f32 v[108:109], v[108:109], 0.5, v[112:113] op_sel_hi:[1,0,1]
	v_pk_fma_f32 v[110:111], v[110:111], 0.5, v[114:115] op_sel_hi:[1,0,1]
	v_cvt_pk_bf16_f32 v116, v108, v109
	v_mul_f32_e32 v109, v109, v109
	v_lshl_add_u64 v[114:115], s[14:15], 0, v[218:219]
	v_fmac_f32_e32 v109, v108, v108
	v_mul_f32_e32 v108, v111, v111
	v_cvt_pk_bf16_f32 v117, v110, v111
	v_lshl_add_u64 v[114:115], v[138:139], 1, v[114:115]
	v_fmac_f32_e32 v108, v110, v110
	v_add_f32_e32 v112, v109, v108
	v_lshlrev_b32_e32 v108, 16, v216
	v_and_b32_e32 v109, 0xffff0000, v216
	v_lshlrev_b32_e32 v110, 16, v217
	v_and_b32_e32 v111, 0xffff0000, v217
	v_pk_fma_f32 v[104:105], v[104:105], 0.5, v[108:109] op_sel_hi:[1,0,1]
	v_pk_fma_f32 v[106:107], v[106:107], 0.5, v[110:111] op_sel_hi:[1,0,1]
	v_cvt_pk_bf16_f32 v118, v104, v105
	v_mul_f32_e32 v105, v105, v105
	v_fmac_f32_e32 v105, v104, v104
	v_mul_f32_e32 v104, v107, v107
	v_fmac_f32_e32 v104, v106, v106
	v_add_f32_e32 v104, v105, v104
	v_add_f32_e32 v109, v112, v104
	v_lshlrev_b32_e32 v104, 16, v214
	v_and_b32_e32 v105, 0xffff0000, v214
	v_lshlrev_b32_e32 v110, 16, v215
	v_and_b32_e32 v111, 0xffff0000, v215
	v_pk_fma_f32 v[102:103], v[102:103], 0.5, v[110:111] op_sel_hi:[1,0,1]
	v_pk_fma_f32 v[100:101], v[100:101], 0.5, v[104:105] op_sel_hi:[1,0,1]
	v_mul_f32_e32 v105, v103, v103
	v_mul_f32_e32 v104, v101, v101
	v_fmac_f32_e32 v104, v100, v100
	v_fmac_f32_e32 v105, v102, v102
	v_add_f32_e32 v104, v104, v105
	v_add_f32_e32 v109, v109, v104
	v_lshlrev_b32_e32 v104, 16, v212
	v_and_b32_e32 v105, 0xffff0000, v212
	v_lshlrev_b32_e32 v110, 16, v213
	v_and_b32_e32 v111, 0xffff0000, v213
	v_pk_fma_f32 v[98:99], v[98:99], 0.5, v[110:111] op_sel_hi:[1,0,1]
	v_pk_fma_f32 v[104:105], v[96:97], 0.5, v[104:105] op_sel_hi:[1,0,1]
	v_mul_f32_e32 v97, v99, v99
	v_mul_f32_e32 v96, v105, v105
	v_fmac_f32_e32 v96, v104, v104
	v_fmac_f32_e32 v97, v98, v98
	v_add_f32_e32 v96, v96, v97
	v_add_f32_e32 v96, v109, v96
	v_mov_b32_e32 v97, v96
	s_nop 1
	v_permlane16_swap_b32_e32 v96, v97
	v_cvt_pk_bf16_f32 v110, v100, v101
	v_cvt_pk_bf16_f32 v111, v102, v103
	v_cvt_pk_bf16_f32 v119, v106, v107
	s_waitcnt lgkmcnt(0)
	v_add_f32_e32 v96, v96, v97
	v_mov_b32_e32 v97, v96
	s_nop 1
	v_permlane32_swap_b32_e32 v96, v97
	v_cvt_pk_bf16_f32 v112, v104, v105
	v_cvt_pk_bf16_f32 v113, v98, v99
	v_lshl_add_u64 v[114:115], v[114:115], 0, v[250:251]
	s_nop 1
	v_permlane16_swap_b32_e32 v116, v118
	v_permlane16_swap_b32_e32 v117, v119
	global_store_dwordx4 v[114:115], v[116:119], off
	s_nop 1
	s_nop 1
	v_permlane16_swap_b32_e32 v110, v112
	v_permlane16_swap_b32_e32 v111, v113
	global_store_dwordx4 v[114:115], v[110:113], off offset:256
	s_nop 1
	s_and_saveexec_b64 s[34:35], vcc
	s_cbranch_execz .LBB0_1739
	v_lshlrev_b64 v[98:99], 6, v[208:209]
	v_lshl_add_u64 v[98:99], s[16:17], 0, v[98:99]
	v_lshl_add_u64 v[98:99], s[30:31], 2, v[98:99]
	s_lshl_b32 s12, s47, 2
	v_lshl_add_u64 v[98:99], v[98:99], 0, s[12:13]
	s_waitcnt lgkmcnt(0)
	v_add_f32_e32 v96, v96, v97
	global_store_dword v[98:99], v96, off
.LBB0_1739:
	s_or_b64 exec, exec, s[34:35]
	s_waitcnt vmcnt(26)
	v_lshlrev_b32_e32 v96, 16, v210
	s_waitcnt lgkmcnt(0)
	v_and_b32_e32 v97, 0xffff0000, v210
	v_lshlrev_b32_e32 v98, 16, v211
	v_and_b32_e32 v99, 0xffff0000, v211
	v_pk_fma_f32 v[92:93], v[92:93], 0.5, v[96:97] op_sel_hi:[1,0,1]
	v_pk_fma_f32 v[94:95], v[94:95], 0.5, v[98:99] op_sel_hi:[1,0,1]
	v_cvt_pk_bf16_f32 v100, v92, v93
	v_mul_f32_e32 v93, v93, v93
	v_lshl_add_u64 v[98:99], s[14:15], 0, v[206:207]
	v_fmac_f32_e32 v93, v92, v92
	v_mul_f32_e32 v92, v95, v95
	v_cvt_pk_bf16_f32 v101, v94, v95
	v_lshl_add_u64 v[98:99], v[138:139], 1, v[98:99]
	v_fmac_f32_e32 v92, v94, v94
	v_add_f32_e32 v96, v93, v92
	v_lshlrev_b32_e32 v92, 16, v204
	v_and_b32_e32 v93, 0xffff0000, v204
	v_lshlrev_b32_e32 v94, 16, v205
	v_and_b32_e32 v95, 0xffff0000, v205
	v_pk_fma_f32 v[88:89], v[88:89], 0.5, v[92:93] op_sel_hi:[1,0,1]
	v_pk_fma_f32 v[90:91], v[90:91], 0.5, v[94:95] op_sel_hi:[1,0,1]
	v_cvt_pk_bf16_f32 v102, v88, v89
	v_mul_f32_e32 v89, v89, v89
	v_fmac_f32_e32 v89, v88, v88
	v_mul_f32_e32 v88, v91, v91
	v_fmac_f32_e32 v88, v90, v90
	v_add_f32_e32 v88, v89, v88
	v_add_f32_e32 v93, v96, v88
	v_lshlrev_b32_e32 v88, 16, v202
	v_and_b32_e32 v89, 0xffff0000, v202
	v_lshlrev_b32_e32 v94, 16, v203
	v_and_b32_e32 v95, 0xffff0000, v203
	v_pk_fma_f32 v[86:87], v[86:87], 0.5, v[94:95] op_sel_hi:[1,0,1]
	v_pk_fma_f32 v[84:85], v[84:85], 0.5, v[88:89] op_sel_hi:[1,0,1]
	v_mul_f32_e32 v89, v87, v87
	v_mul_f32_e32 v88, v85, v85
	v_fmac_f32_e32 v88, v84, v84
	v_fmac_f32_e32 v89, v86, v86
	v_add_f32_e32 v88, v88, v89
	v_add_f32_e32 v93, v93, v88
	v_lshlrev_b32_e32 v88, 16, v200
	v_and_b32_e32 v89, 0xffff0000, v200
	v_lshlrev_b32_e32 v94, 16, v201
	v_and_b32_e32 v95, 0xffff0000, v201
	v_pk_fma_f32 v[82:83], v[82:83], 0.5, v[94:95] op_sel_hi:[1,0,1]
	v_pk_fma_f32 v[88:89], v[80:81], 0.5, v[88:89] op_sel_hi:[1,0,1]
	v_mul_f32_e32 v81, v83, v83
	v_mul_f32_e32 v80, v89, v89
	v_fmac_f32_e32 v80, v88, v88
	v_fmac_f32_e32 v81, v82, v82
	v_add_f32_e32 v80, v80, v81
	v_add_f32_e32 v80, v93, v80
	v_mov_b32_e32 v81, v80
	s_nop 1
	v_permlane16_swap_b32_e32 v80, v81
	v_cvt_pk_bf16_f32 v94, v84, v85
	v_cvt_pk_bf16_f32 v95, v86, v87
	v_cvt_pk_bf16_f32 v103, v90, v91
	s_waitcnt lgkmcnt(0)
	v_add_f32_e32 v80, v80, v81
	v_mov_b32_e32 v81, v80
	s_nop 1
	v_permlane32_swap_b32_e32 v80, v81
	v_cvt_pk_bf16_f32 v96, v88, v89
	v_cvt_pk_bf16_f32 v97, v82, v83
	v_lshl_add_u64 v[98:99], v[98:99], 0, v[250:251]
	s_nop 1
	v_permlane16_swap_b32_e32 v100, v102
	v_permlane16_swap_b32_e32 v101, v103
	global_store_dwordx4 v[98:99], v[100:103], off
	s_nop 1
	s_nop 1
	v_permlane16_swap_b32_e32 v94, v96
	v_permlane16_swap_b32_e32 v95, v97
	global_store_dwordx4 v[98:99], v[94:97], off offset:256
	s_nop 1
	s_and_saveexec_b64 s[34:35], vcc
	s_cbranch_execz .LBB0_1741
	v_lshlrev_b64 v[82:83], 6, v[196:197]
	v_lshl_add_u64 v[82:83], s[16:17], 0, v[82:83]
	v_lshl_add_u64 v[82:83], s[30:31], 2, v[82:83]
	s_lshl_b32 s12, s47, 2
	v_lshl_add_u64 v[82:83], v[82:83], 0, s[12:13]
	s_waitcnt lgkmcnt(0)
	v_add_f32_e32 v80, v80, v81
	global_store_dword v[82:83], v80, off
; #define PG8_GAS __attribute__((address_space(1)))
; __device__ __forceinline__ unsigned pk2_(float lo, float hi) { f32x2c_t v = {lo, hi}; bf16x2c_t b = __builtin_convertvector(v, bf16x2c_t); return __builtin_bit_cast(unsigned, b); }
;     __device__ __forceinline__ void operator()(const f32x4 (&acc)[2][2][4][2], const Unit& u, int wr, int wc, int fr, int fq) const {
;     ...
;         for (int ai = 0; ai < 2; ++ai)
; #pragma unroll
;             for (int m = 0; m < 4; ++m) {
;                 const int r = row0 + ai * HALF + m * 16; const size_t off = (size_t)r * 1024 + col0; float ss = 0.f;
; #pragma unroll
;                 for (int bj = 0; bj < 2; ++bj)
; #pragma unroll
;                     for (int n = 0; n < 2; ++n) {
;                         const u32x2v w0 = bsv[ai][m][bj][n]; f32x4 bs;
;                         bs[0] = __builtin_bit_cast(float, w0.x << 16); bs[1] = __builtin_bit_cast(float, w0.x & 0xffff0000u); bs[2] = __builtin_bit_cast(float, w0.y << 16); bs[3] = __builtin_bit_cast(float, w0.y & 0xffff0000u);
;                         const f32x4 v = bs + acc[ai][bj][m][n] * alpha;
;                         { u32x2v w; w.x = pk2_(v[0], v[1]); w.y = pk2_(v[2], v[3]); *(PG8_GAS u32x2v*)(hb + off + bj * HALF + n * 16) = w; }
;                         ss += (v[0] * v[0] + v[1] * v[1]) + (v[2] * v[2] + v[3] * v[3]);
;                     }
;                 ss += __shfl_xor(ss, 16); ss += __shfl_xor(ss, 32);
;                 if (fq == 0) ((PG8_GAS float*)parts)[(size_t)r * 16 + u.pn * 4 + wc] = ss;
;             }
.LBB0_1741:
	s_or_b64 exec, exec, s[34:35]
	s_waitcnt vmcnt(24)
	v_lshlrev_b32_e32 v80, 16, v198
	s_waitcnt lgkmcnt(0)
	v_and_b32_e32 v81, 0xffff0000, v198
	v_lshlrev_b32_e32 v82, 16, v199
	v_and_b32_e32 v83, 0xffff0000, v199
	v_pk_fma_f32 v[76:77], v[76:77], 0.5, v[80:81] op_sel_hi:[1,0,1]
	v_pk_fma_f32 v[78:79], v[78:79], 0.5, v[82:83] op_sel_hi:[1,0,1]
	v_cvt_pk_bf16_f32 v84, v76, v77
	v_mul_f32_e32 v77, v77, v77
	v_lshl_add_u64 v[82:83], s[14:15], 0, v[194:195]
	v_fmac_f32_e32 v77, v76, v76
	v_mul_f32_e32 v76, v79, v79
	v_cvt_pk_bf16_f32 v85, v78, v79
	v_lshl_add_u64 v[82:83], v[138:139], 1, v[82:83]
	v_fmac_f32_e32 v76, v78, v78
	v_add_f32_e32 v80, v77, v76
	v_lshlrev_b32_e32 v76, 16, v192
	v_and_b32_e32 v77, 0xffff0000, v192
	v_lshlrev_b32_e32 v78, 16, v193
	v_and_b32_e32 v79, 0xffff0000, v193
	v_pk_fma_f32 v[72:73], v[72:73], 0.5, v[76:77] op_sel_hi:[1,0,1]
	v_pk_fma_f32 v[74:75], v[74:75], 0.5, v[78:79] op_sel_hi:[1,0,1]
	v_cvt_pk_bf16_f32 v86, v72, v73
	v_mul_f32_e32 v73, v73, v73
	v_fmac_f32_e32 v73, v72, v72
	v_mul_f32_e32 v72, v75, v75
	v_fmac_f32_e32 v72, v74, v74
	v_add_f32_e32 v72, v73, v72
	v_add_f32_e32 v77, v80, v72
	v_lshlrev_b32_e32 v72, 16, v190
	v_and_b32_e32 v73, 0xffff0000, v190
	v_lshlrev_b32_e32 v78, 16, v191
	v_and_b32_e32 v79, 0xffff0000, v191
	v_pk_fma_f32 v[70:71], v[70:71], 0.5, v[78:79] op_sel_hi:[1,0,1]
	v_pk_fma_f32 v[68:69], v[68:69], 0.5, v[72:73] op_sel_hi:[1,0,1]
	v_mul_f32_e32 v73, v71, v71
	v_mul_f32_e32 v72, v69, v69
	v_fmac_f32_e32 v72, v68, v68
	v_fmac_f32_e32 v73, v70, v70
	v_add_f32_e32 v72, v72, v73
	v_add_f32_e32 v77, v77, v72
	v_lshlrev_b32_e32 v72, 16, v188
	v_and_b32_e32 v73, 0xffff0000, v188
	v_lshlrev_b32_e32 v78, 16, v189
	v_and_b32_e32 v79, 0xffff0000, v189
	v_pk_fma_f32 v[66:67], v[66:67], 0.5, v[78:79] op_sel_hi:[1,0,1]
	v_pk_fma_f32 v[72:73], v[64:65], 0.5, v[72:73] op_sel_hi:[1,0,1]
	v_mul_f32_e32 v65, v67, v67
	v_mul_f32_e32 v64, v73, v73
	v_fmac_f32_e32 v64, v72, v72
	v_fmac_f32_e32 v65, v66, v66
	v_add_f32_e32 v64, v64, v65
	v_add_f32_e32 v64, v77, v64
	v_mov_b32_e32 v65, v64
	s_nop 1
	v_permlane16_swap_b32_e32 v64, v65
	v_cvt_pk_bf16_f32 v78, v68, v69
	v_cvt_pk_bf16_f32 v79, v70, v71
	v_cvt_pk_bf16_f32 v87, v74, v75
	s_waitcnt lgkmcnt(0)
	v_add_f32_e32 v64, v64, v65
	v_mov_b32_e32 v65, v64
	s_nop 1
	v_permlane32_swap_b32_e32 v64, v65
	v_cvt_pk_bf16_f32 v80, v72, v73
	v_cvt_pk_bf16_f32 v81, v66, v67
	v_lshl_add_u64 v[82:83], v[82:83], 0, v[250:251]
	s_nop 1
	v_permlane16_swap_b32_e32 v84, v86
	v_permlane16_swap_b32_e32 v85, v87
	global_store_dwordx4 v[82:83], v[84:87], off
	s_nop 1
	s_nop 1
	v_permlane16_swap_b32_e32 v78, v80
	v_permlane16_swap_b32_e32 v79, v81
	global_store_dwordx4 v[82:83], v[78:81], off offset:256
	s_nop 1
	s_and_saveexec_b64 s[34:35], vcc
	s_cbranch_execz .LBB0_1743
	v_lshlrev_b64 v[66:67], 6, v[184:185]
	v_lshl_add_u64 v[66:67], s[16:17], 0, v[66:67]
	v_lshl_add_u64 v[66:67], s[30:31], 2, v[66:67]
	s_lshl_b32 s12, s47, 2
	v_lshl_add_u64 v[66:67], v[66:67], 0, s[12:13]
	s_waitcnt lgkmcnt(0)
	v_add_f32_e32 v64, v64, v65
	global_store_dword v[66:67], v64, off
.LBB0_1743:
	s_or_b64 exec, exec, s[34:35]
	s_waitcnt vmcnt(22)
	v_lshlrev_b32_e32 v64, 16, v186
	s_waitcnt lgkmcnt(0)
	v_and_b32_e32 v65, 0xffff0000, v186
	v_lshlrev_b32_e32 v66, 16, v187
	v_and_b32_e32 v67, 0xffff0000, v187
	v_pk_fma_f32 v[60:61], v[60:61], 0.5, v[64:65] op_sel_hi:[1,0,1]
	v_pk_fma_f32 v[62:63], v[62:63], 0.5, v[66:67] op_sel_hi:[1,0,1]
	v_cvt_pk_bf16_f32 v68, v60, v61
	v_mul_f32_e32 v61, v61, v61
	v_lshl_add_u64 v[66:67], s[14:15], 0, v[182:183]
	v_fmac_f32_e32 v61, v60, v60
	v_mul_f32_e32 v60, v63, v63
	v_cvt_pk_bf16_f32 v69, v62, v63
	v_lshl_add_u64 v[66:67], v[138:139], 1, v[66:67]
	v_fmac_f32_e32 v60, v62, v62
	v_add_f32_e32 v64, v61, v60
	v_lshlrev_b32_e32 v60, 16, v180
	v_and_b32_e32 v61, 0xffff0000, v180
	v_lshlrev_b32_e32 v62, 16, v181
	v_and_b32_e32 v63, 0xffff0000, v181
	v_pk_fma_f32 v[56:57], v[56:57], 0.5, v[60:61] op_sel_hi:[1,0,1]
	v_pk_fma_f32 v[58:59], v[58:59], 0.5, v[62:63] op_sel_hi:[1,0,1]
	v_cvt_pk_bf16_f32 v70, v56, v57
	v_mul_f32_e32 v57, v57, v57
	v_fmac_f32_e32 v57, v56, v56
	v_mul_f32_e32 v56, v59, v59
	v_fmac_f32_e32 v56, v58, v58
	v_add_f32_e32 v56, v57, v56
	v_add_f32_e32 v61, v64, v56
	v_lshlrev_b32_e32 v56, 16, v178
	v_and_b32_e32 v57, 0xffff0000, v178
	v_lshlrev_b32_e32 v62, 16, v179
	v_and_b32_e32 v63, 0xffff0000, v179
	v_pk_fma_f32 v[54:55], v[54:55], 0.5, v[62:63] op_sel_hi:[1,0,1]
	v_pk_fma_f32 v[52:53], v[52:53], 0.5, v[56:57] op_sel_hi:[1,0,1]
	v_mul_f32_e32 v57, v55, v55
	v_mul_f32_e32 v56, v53, v53
	v_fmac_f32_e32 v56, v52, v52
	v_fmac_f32_e32 v57, v54, v54
	v_add_f32_e32 v56, v56, v57
	v_add_f32_e32 v61, v61, v56
	v_lshlrev_b32_e32 v56, 16, v176
	v_and_b32_e32 v57, 0xffff0000, v176
	v_lshlrev_b32_e32 v62, 16, v177
	v_and_b32_e32 v63, 0xffff0000, v177
	v_pk_fma_f32 v[50:51], v[50:51], 0.5, v[62:63] op_sel_hi:[1,0,1]
	v_pk_fma_f32 v[56:57], v[48:49], 0.5, v[56:57] op_sel_hi:[1,0,1]
	v_mul_f32_e32 v49, v51, v51
	v_mul_f32_e32 v48, v57, v57
	v_fmac_f32_e32 v48, v56, v56
	v_fmac_f32_e32 v49, v50, v50
	v_add_f32_e32 v48, v48, v49
	v_add_f32_e32 v48, v61, v48
	v_mov_b32_e32 v49, v48
	s_nop 1
	v_permlane16_swap_b32_e32 v48, v49
	v_cvt_pk_bf16_f32 v62, v52, v53
	v_cvt_pk_bf16_f32 v63, v54, v55
	v_cvt_pk_bf16_f32 v71, v58, v59
	s_waitcnt lgkmcnt(0)
	v_add_f32_e32 v48, v48, v49
	v_mov_b32_e32 v49, v48
	s_nop 1
	v_permlane32_swap_b32_e32 v48, v49
	v_cvt_pk_bf16_f32 v64, v56, v57
	v_cvt_pk_bf16_f32 v65, v50, v51
	v_lshl_add_u64 v[66:67], v[66:67], 0, v[250:251]
	s_nop 1
	v_permlane16_swap_b32_e32 v68, v70
	v_permlane16_swap_b32_e32 v69, v71
	global_store_dwordx4 v[66:67], v[68:71], off
	s_nop 1
	s_nop 1
	v_permlane16_swap_b32_e32 v62, v64
	v_permlane16_swap_b32_e32 v63, v65
	global_store_dwordx4 v[66:67], v[62:65], off offset:256
	s_nop 1
	s_and_saveexec_b64 s[34:35], vcc
	s_cbranch_execz .LBB0_1745
	v_lshlrev_b64 v[50:51], 6, v[172:173]
	v_lshl_add_u64 v[50:51], s[16:17], 0, v[50:51]
	v_lshl_add_u64 v[50:51], s[30:31], 2, v[50:51]
	s_lshl_b32 s12, s47, 2
	v_lshl_add_u64 v[50:51], v[50:51], 0, s[12:13]
	s_waitcnt lgkmcnt(0)
	v_add_f32_e32 v48, v48, v49
	global_store_dword v[50:51], v48, off
; #define PG8_GAS __attribute__((address_space(1)))
; __device__ __forceinline__ unsigned pk2_(float lo, float hi) { f32x2c_t v = {lo, hi}; bf16x2c_t b = __builtin_convertvector(v, bf16x2c_t); return __builtin_bit_cast(unsigned, b); }
;     __device__ __forceinline__ void operator()(const f32x4 (&acc)[2][2][4][2], const Unit& u, int wr, int wc, int fr, int fq) const {
;     ...
;         for (int ai = 0; ai < 2; ++ai)
; #pragma unroll
;             for (int m = 0; m < 4; ++m) {
;                 const int r = row0 + ai * HALF + m * 16; const size_t off = (size_t)r * 1024 + col0; float ss = 0.f;
; #pragma unroll
;                 for (int bj = 0; bj < 2; ++bj)
; #pragma unroll
;                     for (int n = 0; n < 2; ++n) {
;                         const u32x2v w0 = bsv[ai][m][bj][n]; f32x4 bs;
;                         bs[0] = __builtin_bit_cast(float, w0.x << 16); bs[1] = __builtin_bit_cast(float, w0.x & 0xffff0000u); bs[2] = __builtin_bit_cast(float, w0.y << 16); bs[3] = __builtin_bit_cast(float, w0.y & 0xffff0000u);
;                         const f32x4 v = bs + acc[ai][bj][m][n] * alpha;
;                         { u32x2v w; w.x = pk2_(v[0], v[1]); w.y = pk2_(v[2], v[3]); *(PG8_GAS u32x2v*)(hb + off + bj * HALF + n * 16) = w; }
;                         ss += (v[0] * v[0] + v[1] * v[1]) + (v[2] * v[2] + v[3] * v[3]);
;                     }
;                 ss += __shfl_xor(ss, 16); ss += __shfl_xor(ss, 32);
;                 if (fq == 0) ((PG8_GAS float*)parts)[(size_t)r * 16 + u.pn * 4 + wc] = ss;
;             }
.LBB0_1745:
	s_or_b64 exec, exec, s[34:35]
	s_waitcnt vmcnt(20)
	v_lshlrev_b32_e32 v48, 16, v174
	s_waitcnt lgkmcnt(0)
	v_and_b32_e32 v49, 0xffff0000, v174
	v_lshlrev_b32_e32 v50, 16, v175
	v_and_b32_e32 v51, 0xffff0000, v175
	v_pk_fma_f32 v[44:45], v[44:45], 0.5, v[48:49] op_sel_hi:[1,0,1]
	v_pk_fma_f32 v[46:47], v[46:47], 0.5, v[50:51] op_sel_hi:[1,0,1]
	v_cvt_pk_bf16_f32 v52, v44, v45
	v_mul_f32_e32 v45, v45, v45
	v_lshl_add_u64 v[50:51], s[14:15], 0, v[170:171]
	v_fmac_f32_e32 v45, v44, v44
	v_mul_f32_e32 v44, v47, v47
	v_cvt_pk_bf16_f32 v53, v46, v47
	v_lshl_add_u64 v[50:51], v[138:139], 1, v[50:51]
	v_fmac_f32_e32 v44, v46, v46
	v_add_f32_e32 v48, v45, v44
	v_lshlrev_b32_e32 v44, 16, v168
	v_and_b32_e32 v45, 0xffff0000, v168
	v_lshlrev_b32_e32 v46, 16, v169
	v_and_b32_e32 v47, 0xffff0000, v169
	v_pk_fma_f32 v[40:41], v[40:41], 0.5, v[44:45] op_sel_hi:[1,0,1]
	v_pk_fma_f32 v[42:43], v[42:43], 0.5, v[46:47] op_sel_hi:[1,0,1]
	v_cvt_pk_bf16_f32 v54, v40, v41
	v_mul_f32_e32 v41, v41, v41
	v_fmac_f32_e32 v41, v40, v40
	v_mul_f32_e32 v40, v43, v43
	v_fmac_f32_e32 v40, v42, v42
	v_add_f32_e32 v40, v41, v40
	v_add_f32_e32 v45, v48, v40
	v_lshlrev_b32_e32 v40, 16, v166
	v_and_b32_e32 v41, 0xffff0000, v166
	v_lshlrev_b32_e32 v46, 16, v167
	v_and_b32_e32 v47, 0xffff0000, v167
	v_pk_fma_f32 v[38:39], v[38:39], 0.5, v[46:47] op_sel_hi:[1,0,1]
	v_pk_fma_f32 v[36:37], v[36:37], 0.5, v[40:41] op_sel_hi:[1,0,1]
	v_mul_f32_e32 v41, v39, v39
	v_mul_f32_e32 v40, v37, v37
	v_fmac_f32_e32 v40, v36, v36
	v_fmac_f32_e32 v41, v38, v38
	v_add_f32_e32 v40, v40, v41
	v_add_f32_e32 v45, v45, v40
	v_lshlrev_b32_e32 v40, 16, v164
	v_and_b32_e32 v41, 0xffff0000, v164
	v_lshlrev_b32_e32 v46, 16, v165
	v_and_b32_e32 v47, 0xffff0000, v165
	v_pk_fma_f32 v[34:35], v[34:35], 0.5, v[46:47] op_sel_hi:[1,0,1]
	v_pk_fma_f32 v[40:41], v[32:33], 0.5, v[40:41] op_sel_hi:[1,0,1]
	v_mul_f32_e32 v33, v35, v35
	v_mul_f32_e32 v32, v41, v41
	v_fmac_f32_e32 v32, v40, v40
	v_fmac_f32_e32 v33, v34, v34
	v_add_f32_e32 v32, v32, v33
	v_add_f32_e32 v32, v45, v32
	v_mov_b32_e32 v33, v32
	s_nop 1
	v_permlane16_swap_b32_e32 v32, v33
	v_cvt_pk_bf16_f32 v46, v36, v37
	v_cvt_pk_bf16_f32 v47, v38, v39
	v_cvt_pk_bf16_f32 v55, v42, v43
	s_waitcnt lgkmcnt(0)
	v_add_f32_e32 v32, v32, v33
	v_mov_b32_e32 v33, v32
	s_nop 1
	v_permlane32_swap_b32_e32 v32, v33
	v_cvt_pk_bf16_f32 v48, v40, v41
	v_cvt_pk_bf16_f32 v49, v34, v35
	v_lshl_add_u64 v[50:51], v[50:51], 0, v[250:251]
	s_nop 1
	v_permlane16_swap_b32_e32 v52, v54
	v_permlane16_swap_b32_e32 v53, v55
	global_store_dwordx4 v[50:51], v[52:55], off
	s_nop 1
	s_nop 1
	v_permlane16_swap_b32_e32 v46, v48
	v_permlane16_swap_b32_e32 v47, v49
	global_store_dwordx4 v[50:51], v[46:49], off offset:256
	s_nop 1
	s_and_saveexec_b64 s[34:35], vcc
	s_cbranch_execz .LBB0_1747
	v_lshlrev_b64 v[34:35], 6, v[160:161]
	v_lshl_add_u64 v[34:35], s[16:17], 0, v[34:35]
	v_lshl_add_u64 v[34:35], s[30:31], 2, v[34:35]
	s_lshl_b32 s12, s47, 2
	v_lshl_add_u64 v[34:35], v[34:35], 0, s[12:13]
	s_waitcnt lgkmcnt(0)
	v_add_f32_e32 v32, v32, v33
	global_store_dword v[34:35], v32, off
; #define PG8_GAS __attribute__((address_space(1)))
; __device__ __forceinline__ unsigned pk2_(float lo, float hi) { f32x2c_t v = {lo, hi}; bf16x2c_t b = __builtin_convertvector(v, bf16x2c_t); return __builtin_bit_cast(unsigned, b); }
;     __device__ __forceinline__ void operator()(const f32x4 (&acc)[2][2][4][2], const Unit& u, int wr, int wc, int fr, int fq) const {
;     ...
;         for (int ai = 0; ai < 2; ++ai)
; #pragma unroll
;             for (int m = 0; m < 4; ++m) {
;                 const int r = row0 + ai * HALF + m * 16; const size_t off = (size_t)r * 1024 + col0; float ss = 0.f;
; #pragma unroll
;                 for (int bj = 0; bj < 2; ++bj)
; #pragma unroll
;                     for (int n = 0; n < 2; ++n) {
;                         const u32x2v w0 = bsv[ai][m][bj][n]; f32x4 bs;
;                         bs[0] = __builtin_bit_cast(float, w0.x << 16); bs[1] = __builtin_bit_cast(float, w0.x & 0xffff0000u); bs[2] = __builtin_bit_cast(float, w0.y << 16); bs[3] = __builtin_bit_cast(float, w0.y & 0xffff0000u);
;                         const f32x4 v = bs + acc[ai][bj][m][n] * alpha;
;                         { u32x2v w; w.x = pk2_(v[0], v[1]); w.y = pk2_(v[2], v[3]); *(PG8_GAS u32x2v*)(hb + off + bj * HALF + n * 16) = w; }
;                         ss += (v[0] * v[0] + v[1] * v[1]) + (v[2] * v[2] + v[3] * v[3]);
;                     }
;                 ss += __shfl_xor(ss, 16); ss += __shfl_xor(ss, 32);
;                 if (fq == 0) ((PG8_GAS float*)parts)[(size_t)r * 16 + u.pn * 4 + wc] = ss;
;             }
.LBB0_1747:
	s_or_b64 exec, exec, s[34:35]
	s_waitcnt vmcnt(18)
	v_lshlrev_b32_e32 v32, 16, v162
	s_waitcnt lgkmcnt(0)
	v_and_b32_e32 v33, 0xffff0000, v162
	v_lshlrev_b32_e32 v34, 16, v163
	v_and_b32_e32 v35, 0xffff0000, v163
	v_pk_fma_f32 v[28:29], v[28:29], 0.5, v[32:33] op_sel_hi:[1,0,1]
	v_pk_fma_f32 v[30:31], v[30:31], 0.5, v[34:35] op_sel_hi:[1,0,1]
	v_cvt_pk_bf16_f32 v36, v28, v29
	v_mul_f32_e32 v29, v29, v29
	v_lshl_add_u64 v[34:35], s[14:15], 0, v[158:159]
	v_fmac_f32_e32 v29, v28, v28
	v_mul_f32_e32 v28, v31, v31
	v_cvt_pk_bf16_f32 v37, v30, v31
	v_lshl_add_u64 v[34:35], v[138:139], 1, v[34:35]
	v_fmac_f32_e32 v28, v30, v30
	v_add_f32_e32 v32, v29, v28
	v_lshlrev_b32_e32 v28, 16, v156
	v_and_b32_e32 v29, 0xffff0000, v156
	v_lshlrev_b32_e32 v30, 16, v157
	v_and_b32_e32 v31, 0xffff0000, v157
	v_pk_fma_f32 v[24:25], v[24:25], 0.5, v[28:29] op_sel_hi:[1,0,1]
	v_pk_fma_f32 v[26:27], v[26:27], 0.5, v[30:31] op_sel_hi:[1,0,1]
	v_cvt_pk_bf16_f32 v38, v24, v25
	v_mul_f32_e32 v25, v25, v25
	v_fmac_f32_e32 v25, v24, v24
	v_mul_f32_e32 v24, v27, v27
	v_fmac_f32_e32 v24, v26, v26
	v_add_f32_e32 v24, v25, v24
	v_add_f32_e32 v29, v32, v24
	v_lshlrev_b32_e32 v24, 16, v154
	v_and_b32_e32 v25, 0xffff0000, v154
	v_lshlrev_b32_e32 v30, 16, v155
	v_and_b32_e32 v31, 0xffff0000, v155
	v_pk_fma_f32 v[22:23], v[22:23], 0.5, v[30:31] op_sel_hi:[1,0,1]
	v_pk_fma_f32 v[20:21], v[20:21], 0.5, v[24:25] op_sel_hi:[1,0,1]
	v_mul_f32_e32 v25, v23, v23
	v_mul_f32_e32 v24, v21, v21
	v_fmac_f32_e32 v24, v20, v20
	v_fmac_f32_e32 v25, v22, v22
	v_add_f32_e32 v24, v24, v25
	v_add_f32_e32 v29, v29, v24
	v_lshlrev_b32_e32 v24, 16, v152
	v_and_b32_e32 v25, 0xffff0000, v152
	v_lshlrev_b32_e32 v30, 16, v153
	v_and_b32_e32 v31, 0xffff0000, v153
	v_pk_fma_f32 v[18:19], v[18:19], 0.5, v[30:31] op_sel_hi:[1,0,1]
	v_pk_fma_f32 v[24:25], v[16:17], 0.5, v[24:25] op_sel_hi:[1,0,1]
	v_mul_f32_e32 v17, v19, v19
	v_mul_f32_e32 v16, v25, v25
	v_fmac_f32_e32 v16, v24, v24
	v_fmac_f32_e32 v17, v18, v18
	v_add_f32_e32 v16, v16, v17
	v_add_f32_e32 v16, v29, v16
	v_mov_b32_e32 v17, v16
	s_nop 1
	v_permlane16_swap_b32_e32 v16, v17
	v_cvt_pk_bf16_f32 v30, v20, v21
	v_cvt_pk_bf16_f32 v31, v22, v23
	v_cvt_pk_bf16_f32 v39, v26, v27
	s_waitcnt lgkmcnt(0)
	v_add_f32_e32 v16, v16, v17
	v_mov_b32_e32 v17, v16
	s_nop 1
	v_permlane32_swap_b32_e32 v16, v17
	v_cvt_pk_bf16_f32 v32, v24, v25
	v_cvt_pk_bf16_f32 v33, v18, v19
	v_lshl_add_u64 v[34:35], v[34:35], 0, v[250:251]
	s_nop 1
	v_permlane16_swap_b32_e32 v36, v38
	v_permlane16_swap_b32_e32 v37, v39
	global_store_dwordx4 v[34:35], v[36:39], off
	s_nop 1
	s_nop 1
	v_permlane16_swap_b32_e32 v30, v32
	v_permlane16_swap_b32_e32 v31, v33
	global_store_dwordx4 v[34:35], v[30:33], off offset:256
	s_nop 1
	s_and_saveexec_b64 s[34:35], vcc
	s_cbranch_execz .LBB0_1749
	v_lshlrev_b64 v[18:19], 6, v[148:149]
	v_lshl_add_u64 v[18:19], s[16:17], 0, v[18:19]
	v_lshl_add_u64 v[18:19], s[30:31], 2, v[18:19]
	s_lshl_b32 s12, s47, 2
	v_lshl_add_u64 v[18:19], v[18:19], 0, s[12:13]
	s_waitcnt lgkmcnt(0)
	v_add_f32_e32 v16, v16, v17
	global_store_dword v[18:19], v16, off
.LBB0_1749:
	s_or_b64 exec, exec, s[34:35]
	s_waitcnt vmcnt(16)
	v_lshlrev_b32_e32 v16, 16, v150
	s_waitcnt lgkmcnt(0)
	v_and_b32_e32 v17, 0xffff0000, v150
	v_lshlrev_b32_e32 v18, 16, v151
	v_and_b32_e32 v19, 0xffff0000, v151
	v_pk_fma_f32 v[12:13], v[12:13], 0.5, v[16:17] op_sel_hi:[1,0,1]
	v_pk_fma_f32 v[14:15], v[14:15], 0.5, v[18:19] op_sel_hi:[1,0,1]
	v_cvt_pk_bf16_f32 v20, v12, v13
	v_mul_f32_e32 v13, v13, v13
	v_lshl_add_u64 v[18:19], s[14:15], 0, v[146:147]
	v_fmac_f32_e32 v13, v12, v12
	v_mul_f32_e32 v12, v15, v15
	v_cvt_pk_bf16_f32 v21, v14, v15
	v_lshl_add_u64 v[18:19], v[138:139], 1, v[18:19]
	v_fmac_f32_e32 v12, v14, v14
	v_add_f32_e32 v16, v13, v12
	v_lshlrev_b32_e32 v12, 16, v144
	v_and_b32_e32 v13, 0xffff0000, v144
	v_lshlrev_b32_e32 v14, 16, v145
	v_and_b32_e32 v15, 0xffff0000, v145
	v_pk_fma_f32 v[8:9], v[8:9], 0.5, v[12:13] op_sel_hi:[1,0,1]
	v_pk_fma_f32 v[10:11], v[10:11], 0.5, v[14:15] op_sel_hi:[1,0,1]
	v_cvt_pk_bf16_f32 v22, v8, v9
	v_mul_f32_e32 v9, v9, v9
	v_fmac_f32_e32 v9, v8, v8
	v_mul_f32_e32 v8, v11, v11
	v_fmac_f32_e32 v8, v10, v10
	v_add_f32_e32 v8, v9, v8
	v_add_f32_e32 v13, v16, v8
	v_lshlrev_b32_e32 v8, 16, v142
	v_and_b32_e32 v9, 0xffff0000, v142
	v_lshlrev_b32_e32 v14, 16, v143
	v_and_b32_e32 v15, 0xffff0000, v143
	v_pk_fma_f32 v[6:7], v[6:7], 0.5, v[14:15] op_sel_hi:[1,0,1]
	v_pk_fma_f32 v[4:5], v[4:5], 0.5, v[8:9] op_sel_hi:[1,0,1]
	v_mul_f32_e32 v9, v7, v7
	v_mul_f32_e32 v8, v5, v5
	v_fmac_f32_e32 v8, v4, v4
	v_fmac_f32_e32 v9, v6, v6
	v_add_f32_e32 v8, v8, v9
	v_add_f32_e32 v13, v13, v8
	v_lshlrev_b32_e32 v8, 16, v140
	v_and_b32_e32 v9, 0xffff0000, v140
	v_lshlrev_b32_e32 v14, 16, v141
	v_and_b32_e32 v15, 0xffff0000, v141
	v_pk_fma_f32 v[2:3], v[2:3], 0.5, v[14:15] op_sel_hi:[1,0,1]
	v_pk_fma_f32 v[8:9], v[0:1], 0.5, v[8:9] op_sel_hi:[1,0,1]
	v_mul_f32_e32 v1, v3, v3
	v_mul_f32_e32 v0, v9, v9
	v_fmac_f32_e32 v0, v8, v8
	v_fmac_f32_e32 v1, v2, v2
	v_add_f32_e32 v0, v0, v1
	v_add_f32_e32 v0, v13, v0
	v_mov_b32_e32 v1, v0
	s_nop 1
	v_permlane16_swap_b32_e32 v0, v1
	v_cvt_pk_bf16_f32 v14, v4, v5
	v_cvt_pk_bf16_f32 v15, v6, v7
	v_cvt_pk_bf16_f32 v23, v10, v11
	s_waitcnt lgkmcnt(0)
	v_add_f32_e32 v0, v0, v1
	v_mov_b32_e32 v1, v0
	s_nop 1
	v_permlane32_swap_b32_e32 v0, v1
	v_cvt_pk_bf16_f32 v16, v8, v9
	v_cvt_pk_bf16_f32 v17, v2, v3
	v_lshl_add_u64 v[18:19], v[18:19], 0, v[250:251]
	s_nop 1
	v_permlane16_swap_b32_e32 v20, v22
	v_permlane16_swap_b32_e32 v21, v23
	global_store_dwordx4 v[18:19], v[20:23], off
	s_nop 1
	s_nop 1
	v_permlane16_swap_b32_e32 v14, v16
	v_permlane16_swap_b32_e32 v15, v17
	global_store_dwordx4 v[18:19], v[14:17], off offset:256
	s_nop 1
	s_and_saveexec_b64 s[34:35], vcc
	s_cbranch_execz .LBB0_1751
	v_lshlrev_b64 v[2:3], 6, v[136:137]
	v_lshl_add_u64 v[2:3], s[16:17], 0, v[2:3]
	v_lshl_add_u64 v[2:3], s[30:31], 2, v[2:3]
	s_lshl_b32 s12, s47, 2
	v_lshl_add_u64 v[2:3], v[2:3], 0, s[12:13]
	s_waitcnt lgkmcnt(0)
	v_add_f32_e32 v0, v0, v1
	global_store_dword v[2:3], v0, off
